# glu second GEMM loop also unrolled by two (second address set borrows the dead operand-pointer registers)
# baseline (speedup 1.0000x reference)
.LBB0_114:
	v_mov_b32_e32 v6, v181
	s_ashr_i32 s93, s92, 6
	v_lshrrev_b32_e32 v7, 4, v6
	v_lshlrev_b32_e32 v1, 6, v6
	v_xor_b32_e32 v0, v7, v6
	v_and_b32_e32 v8, 0x3c0, v1
	v_lshlrev_b32_e32 v1, 7, v6
	s_bfe_u32 s94, s92, 0x20006
	s_and_b32 s86, s91, 63
	s_and_b32 s95, s92, 63
	s_and_b32 s21, s93, -4
	v_lshlrev_b32_e32 v0, 3, v0
	v_and_b32_e32 v1, 0xfffffc00, v1
	s_lshl_b32 s20, s86, 19
	s_or_b32 s58, s21, s94
	s_lshl_b32 s21, s95, 19
	v_and_or_b32 v0, v0, 56, v1
	s_waitcnt lgkmcnt(0)
	s_add_u32 s60, s3, s21
	v_ashrrev_i32_e32 v1, 31, v0
	v_lshl_add_u32 v129, v6, 4, 0
	s_addc_u32 s61, s90, 0
	v_lshlrev_b64 v[0:1], 1, v[0:1]
	v_readfirstlane_b32 s21, v129
	v_add_u32_e32 v9, 0x2000, v129
	v_lshl_add_u64 v[2:3], s[60:61], 0, v[0:1]
	s_mov_b32 m0, s21
	v_readfirstlane_b32 s21, v9
	v_add_u32_e32 v9, 0x4000, v129
	s_barrier
	global_load_lds_dwordx4 v[2:3], off
	v_lshl_add_u64 v[4:5], v[2:3], 0, s[10:11]
	s_mov_b32 m0, s21
	v_readfirstlane_b32 s21, v9
	global_load_lds_dwordx4 v[4:5], off
	v_lshl_add_u64 v[4:5], v[2:3], 0, s[12:13]
	s_mov_b32 m0, s21
	s_ashr_i32 s59, s58, 31
	global_load_lds_dwordx4 v[4:5], off
	v_add_u32_e32 v4, 0x6000, v129
	s_lshl_b64 s[88:89], s[58:59], 19
	v_readfirstlane_b32 s21, v4
	v_lshl_add_u64 v[2:3], v[2:3], 0, s[14:15]
	s_mov_b32 m0, s21
	s_add_u32 s88, s34, s88
	global_load_lds_dwordx4 v[2:3], off
	v_add_u32_e32 v2, 0x8000, v129
	s_addc_u32 s89, s35, s89
	v_readfirstlane_b32 s21, v2
	v_add_u32_e32 v4, 0xa000, v129
	v_lshl_add_u64 v[134:135], s[88:89], 0, v[0:1]
	s_mov_b32 m0, s21
	v_readfirstlane_b32 s21, v4
	v_add_u32_e32 v4, 0xc000, v129
	global_load_lds_dwordx4 v[134:135], off
	v_lshl_add_u64 v[2:3], v[134:135], 0, s[10:11]
	s_mov_b32 m0, s21
	v_readfirstlane_b32 s21, v4
	v_add_u32_e32 v4, 0xe000, v129
	global_load_lds_dwordx4 v[2:3], off
	v_lshl_add_u64 v[2:3], v[134:135], 0, s[12:13]
	s_mov_b32 m0, s21
	v_readfirstlane_b32 s21, v4
	global_load_lds_dwordx4 v[2:3], off
	v_lshl_add_u64 v[2:3], v[134:135], 0, s[14:15]
	s_mov_b32 m0, s21
	v_ashrrev_i32_e32 v4, 6, v6
	global_load_lds_dwordx4 v[2:3], off
	v_lshrrev_b32_e32 v5, 30, v4
	v_add_u32_e32 v5, v4, v5
	v_bfe_u32 v2, v6, 4, 2
	v_bfe_u32 v3, v6, 1, 3
	v_and_b32_e32 v6, 0x7fffc, v5
	v_sub_u32_e32 v4, v4, v6
	v_lshlrev_b32_e32 v139, 13, v4
	v_bitop3_b32 v4, v7, v3, 3 bitop3:0x6c
	v_bitop3_b32 v2, v2, v3, 4 bitop3:0x36
	s_add_u32 s60, s34, s20
	v_lshlrev_b32_e32 v5, 12, v5
	v_lshlrev_b32_e32 v4, 3, v4
	v_lshlrev_b32_e32 v2, 3, v2
	s_addc_u32 s61, s35, 0
	v_and_b32_e32 v138, 0xffffc000, v5
	v_lshl_add_u64 v[136:137], s[60:61], 0, v[0:1]
	s_mov_b64 s[60:61], 0
	v_lshlrev_b32_e32 v140, 1, v8
	v_lshlrev_b32_e32 v141, 1, v4
	v_lshlrev_b32_e32 v142, 1, v2
	s_mov_b32 s87, 0
	s_mov_b32 s59, 0
	v_mov_b32_e32 v8, v128
	v_mov_b32_e32 v9, v128
	v_mov_b32_e32 v10, v128
	v_mov_b32_e32 v11, v128
	v_mov_b32_e32 v20, v128
	v_mov_b32_e32 v21, v128
	v_mov_b32_e32 v22, v128
	v_mov_b32_e32 v23, v128
	v_mov_b32_e32 v0, v128
	v_mov_b32_e32 v1, v128
	v_mov_b32_e32 v2, v128
	v_mov_b32_e32 v3, v128
	v_mov_b32_e32 v4, v128
	v_mov_b32_e32 v5, v128
	v_mov_b32_e32 v6, v128
	v_mov_b32_e32 v7, v128
	v_mov_b32_e32 v12, v128
	v_mov_b32_e32 v13, v128
	v_mov_b32_e32 v14, v128
	v_mov_b32_e32 v15, v128
	v_mov_b32_e32 v24, v128
	v_mov_b32_e32 v25, v128
	v_mov_b32_e32 v26, v128
	v_mov_b32_e32 v27, v128
	v_mov_b32_e32 v16, v128
	v_mov_b32_e32 v17, v128
	v_mov_b32_e32 v18, v128
	v_mov_b32_e32 v19, v128
	v_mov_b32_e32 v28, v128
	v_mov_b32_e32 v29, v128
	v_mov_b32_e32 v30, v128
	v_mov_b32_e32 v31, v128
	v_mov_b32_e32 v32, v128
	v_mov_b32_e32 v33, v128
	v_mov_b32_e32 v34, v128
	v_mov_b32_e32 v35, v128
	v_mov_b32_e32 v40, v128
	v_mov_b32_e32 v41, v128
	v_mov_b32_e32 v42, v128
	v_mov_b32_e32 v43, v128
	v_mov_b32_e32 v36, v128
	v_mov_b32_e32 v37, v128
	v_mov_b32_e32 v38, v128
	v_mov_b32_e32 v39, v128
	v_mov_b32_e32 v44, v128
	v_mov_b32_e32 v45, v128
	v_mov_b32_e32 v46, v128
	v_mov_b32_e32 v47, v128
	v_mov_b32_e32 v48, v128
	v_mov_b32_e32 v49, v128
	v_mov_b32_e32 v50, v128
	v_mov_b32_e32 v51, v128
	v_mov_b32_e32 v56, v128
	v_mov_b32_e32 v57, v128
	v_mov_b32_e32 v58, v128
	v_mov_b32_e32 v59, v128
	v_mov_b32_e32 v52, v128
	v_mov_b32_e32 v53, v128
	v_mov_b32_e32 v54, v128
	v_mov_b32_e32 v55, v128
	v_mov_b32_e32 v60, v128
	v_mov_b32_e32 v61, v128
	v_mov_b32_e32 v62, v128
	v_mov_b32_e32 v63, v128
	v_mov_b32_e32 v64, v128
	v_mov_b32_e32 v65, v128
	v_mov_b32_e32 v66, v128
	v_mov_b32_e32 v67, v128
	v_mov_b32_e32 v72, v128
	v_mov_b32_e32 v73, v128
	v_mov_b32_e32 v74, v128
	v_mov_b32_e32 v75, v128
	v_mov_b32_e32 v68, v128
	v_mov_b32_e32 v69, v128
	v_mov_b32_e32 v70, v128
	v_mov_b32_e32 v71, v128
	v_mov_b32_e32 v76, v128
	v_mov_b32_e32 v77, v128
	v_mov_b32_e32 v78, v128
	v_mov_b32_e32 v79, v128
	v_mov_b32_e32 v80, v128
	v_mov_b32_e32 v81, v128
	v_mov_b32_e32 v82, v128
	v_mov_b32_e32 v83, v128
	v_mov_b32_e32 v88, v128
	v_mov_b32_e32 v89, v128
	v_mov_b32_e32 v90, v128
	v_mov_b32_e32 v91, v128
	v_mov_b32_e32 v84, v128
	v_mov_b32_e32 v85, v128
	v_mov_b32_e32 v86, v128
	v_mov_b32_e32 v87, v128
	v_mov_b32_e32 v92, v128
	v_mov_b32_e32 v93, v128
	v_mov_b32_e32 v94, v128
	v_mov_b32_e32 v95, v128
	v_mov_b32_e32 v96, v128
	v_mov_b32_e32 v97, v128
	v_mov_b32_e32 v98, v128
	v_mov_b32_e32 v99, v128
	v_mov_b32_e32 v104, v128
	v_mov_b32_e32 v105, v128
	v_mov_b32_e32 v106, v128
	v_mov_b32_e32 v107, v128
	v_mov_b32_e32 v100, v128
	v_mov_b32_e32 v101, v128
	v_mov_b32_e32 v102, v128
	v_mov_b32_e32 v103, v128
	v_mov_b32_e32 v108, v128
	v_mov_b32_e32 v109, v128
	v_mov_b32_e32 v110, v128
	v_mov_b32_e32 v111, v128
	v_mov_b32_e32 v112, v128
	v_mov_b32_e32 v113, v128
	v_mov_b32_e32 v114, v128
	v_mov_b32_e32 v115, v128
	v_mov_b32_e32 v120, v128
	v_mov_b32_e32 v121, v128
	v_mov_b32_e32 v122, v128
	v_mov_b32_e32 v123, v128
	v_mov_b32_e32 v116, v128
	v_mov_b32_e32 v117, v128
	v_mov_b32_e32 v118, v128
	v_mov_b32_e32 v119, v128
	v_mov_b32_e32 v124, v128
	v_mov_b32_e32 v125, v128
	v_mov_b32_e32 v126, v128
	v_mov_b32_e32 v127, v128
	s_waitcnt vmcnt(0) lgkmcnt(0)
	s_barrier
	v_add3_u32 v143, v138, v140, v141
	v_add3_u32 v180, v139, v140, v141
	v_add3_u32 v155, v138, v140, v142
	v_add3_u32 v222, v139, v140, v142
	v_readfirstlane_b32 s87, v129
	ds_read_b128 v[156:159], v143
	ds_read_b128 v[160:163], v143 offset:2048
	ds_read_b128 v[164:167], v143 offset:4096
	ds_read_b128 v[168:171], v143 offset:6144
	ds_read_b128 v[190:193], v180 offset:32768
	ds_read_b128 v[194:197], v180 offset:34816
	ds_read_b128 v[198:201], v180 offset:36864
	ds_read_b128 v[202:205], v180 offset:38912
	s_mov_b32 s59, 0
	s_mov_b64 s[60:61], s[34:35]
	v_subrev_u32_e32 v144, s34, v136
	v_subrev_u32_e32 v145, s34, v134
	v_xor_b32_e32 v223, 0x10000, v143
	v_xor_b32_e32 v224, 0x10000, v155
	v_xor_b32_e32 v225, 0x10000, v180
	v_xor_b32_e32 v226, 0x10000, v222
	s_add_u32 s87, s87, 0x10000
	s_mov_b32 m0, s87
	s_add_u32 s88, s60, s16
	s_addc_u32 s89, s61, s17
	global_load_lds_dwordx4 v144, s[88:89]
	s_add_u32 m0, s87, 0x2000
	s_add_u32 s88, s60, s18
	s_addc_u32 s89, s61, s19
	global_load_lds_dwordx4 v144, s[88:89]
	s_add_u32 m0, s87, 0x4000
	s_add_u32 s88, s60, s22
	s_addc_u32 s89, s61, s23
	global_load_lds_dwordx4 v144, s[88:89]
	s_add_u32 m0, s87, 0x6000
	s_add_u32 s88, s60, s40
	s_addc_u32 s89, s61, s41
	global_load_lds_dwordx4 v144, s[88:89]
	s_add_u32 m0, s87, 0x8000
	s_add_u32 s88, s60, s42
	s_addc_u32 s89, s61, s43
	global_load_lds_dwordx4 v145, s[88:89]
	s_add_u32 m0, s87, 0xa000
	s_add_u32 s88, s60, s52
	s_addc_u32 s89, s61, s53
	global_load_lds_dwordx4 v145, s[88:89]
	s_add_u32 m0, s87, 0xc000
	s_add_u32 s88, s60, s54
	s_addc_u32 s89, s61, s55
	global_load_lds_dwordx4 v145, s[88:89]
	s_add_u32 m0, s87, 0xe000
	s_add_u32 s88, s60, s56
	s_addc_u32 s89, s61, s57
	global_load_lds_dwordx4 v145, s[88:89]
	s_branch .Lg0_entry

.LBB0_263:
	s_ashr_i32 s21, s58, 2
	v_mov_b32_e32 v6, v181
	s_and_b32 s6, s58, 7
	s_and_b32 s21, s21, -8
	s_or_b32 s48, s21, s6
	v_lshrrev_b32_e32 v7, 4, v6
	v_lshlrev_b32_e32 v1, 6, v6
	v_xor_b32_e32 v0, v7, v6
	v_and_b32_e32 v8, 0x3c0, v1
	v_lshlrev_b32_e32 v1, 8, v6
	s_ashr_i32 s49, s48, 31
	v_lshlrev_b32_e32 v0, 3, v0
	v_and_b32_e32 v1, 0xfffff800, v1
	s_and_b32 s20, s57, 7
	s_bfe_u32 s6, s58, 0x20003
	s_lshl_b64 s[50:51], s[48:49], 20
	v_and_or_b32 v0, v0, 56, v1
	s_add_u32 s50, s3, s50
	v_ashrrev_i32_e32 v1, 31, v0
	s_addc_u32 s51, s54, s51
	v_lshlrev_b64 v[0:1], 1, v[0:1]
	v_lshl_add_u32 v135, v6, 4, 0
	v_lshl_add_u64 v[2:3], s[50:51], 0, v[0:1]
	v_readfirstlane_b32 s50, v135
	v_add_u32_e32 v9, 0x2000, v135
	s_mov_b32 m0, s50
	v_readfirstlane_b32 s50, v9
	v_add_u32_e32 v9, 0x4000, v135
	s_waitcnt lgkmcnt(0)
	s_barrier
	global_load_lds_dwordx4 v[2:3], off
	v_lshl_add_u64 v[4:5], v[2:3], 0, s[8:9]
	s_mov_b32 m0, s50
	v_readfirstlane_b32 s50, v9
	global_load_lds_dwordx4 v[4:5], off
	v_lshl_add_u64 v[4:5], v[2:3], 0, s[10:11]
	s_mov_b32 m0, s50
	s_lshl_b32 s49, s6, 20
	global_load_lds_dwordx4 v[4:5], off
	v_add_u32_e32 v4, 0x6000, v135
	s_add_u32 s52, s55, s49
	v_readfirstlane_b32 s50, v4
	v_add_u32_e32 v4, 0x8000, v135
	s_addc_u32 s53, s56, 0
	v_lshl_add_u64 v[2:3], v[2:3], 0, s[12:13]
	s_mov_b32 m0, s50
	v_readfirstlane_b32 s50, v4
	v_add_u32_e32 v9, 0xa000, v135
	global_load_lds_dwordx4 v[2:3], off
	v_lshl_add_u64 v[2:3], s[52:53], 0, v[0:1]
	s_mov_b32 m0, s50
	v_readfirstlane_b32 s50, v9
	v_add_u32_e32 v9, 0xc000, v135
	global_load_lds_dwordx4 v[2:3], off
	v_lshl_add_u64 v[4:5], v[2:3], 0, s[8:9]
	s_mov_b32 m0, s50
	v_readfirstlane_b32 s50, v9
	global_load_lds_dwordx4 v[4:5], off
	v_lshl_add_u64 v[4:5], v[2:3], 0, s[10:11]
	s_mov_b32 m0, s50
	v_lshl_add_u64 v[2:3], v[2:3], 0, s[12:13]
	global_load_lds_dwordx4 v[4:5], off
	v_add_u32_e32 v4, 0xe000, v135
	v_mov_b32_e32 v12, 0
	v_readfirstlane_b32 s50, v4
	s_mov_b32 m0, s50
	v_ashrrev_i32_e32 v4, 6, v6
	global_load_lds_dwordx4 v[2:3], off
	s_or_b32 s50, s21, s20
	v_lshrrev_b32_e32 v5, 30, v4
	s_ashr_i32 s51, s50, 31
	v_add_u32_e32 v5, v4, v5
	s_lshl_b64 s[50:51], s[50:51], 20
	v_bfe_u32 v2, v6, 4, 2
	v_bfe_u32 v3, v6, 1, 3
	v_and_b32_e32 v6, 0x7fffc, v5
	s_add_u32 s50, s34, s50
	v_sub_u32_e32 v4, v4, v6
	s_addc_u32 s51, s35, s51
	v_lshlrev_b32_e32 v137, 13, v4
	v_bitop3_b32 v4, v7, v3, 3 bitop3:0x6c
	v_bitop3_b32 v2, v2, v3, 4 bitop3:0x36
	v_lshl_add_u64 v[130:131], s[50:51], 0, v[0:1]
	s_add_u32 s50, s34, s49
	v_lshlrev_b32_e32 v5, 12, v5
	v_lshlrev_b32_e32 v4, 3, v4
	v_lshlrev_b32_e32 v2, 3, v2
	s_addc_u32 s51, s35, 0
	v_and_b32_e32 v136, 0xffffc000, v5
	v_lshl_add_u64 v[132:133], s[50:51], 0, v[0:1]
	s_mov_b64 s[50:51], 0
	v_lshlrev_b32_e32 v138, 1, v8
	v_lshlrev_b32_e32 v139, 1, v4
	v_lshlrev_b32_e32 v140, 1, v2
	s_mov_b32 s59, 0
	s_mov_b32 s49, 0
	v_mov_b32_e32 v13, v12
	v_mov_b32_e32 v14, v12
	v_mov_b32_e32 v15, v12
	v_mov_b32_e32 v24, v12
	v_mov_b32_e32 v25, v12
	v_mov_b32_e32 v26, v12
	v_mov_b32_e32 v27, v12
	v_mov_b32_e32 v0, v12
	v_mov_b32_e32 v1, v12
	v_mov_b32_e32 v2, v12
	v_mov_b32_e32 v3, v12
	v_mov_b32_e32 v4, v12
	v_mov_b32_e32 v5, v12
	v_mov_b32_e32 v6, v12
	v_mov_b32_e32 v7, v12
	v_mov_b32_e32 v8, v12
	v_mov_b32_e32 v9, v12
	v_mov_b32_e32 v10, v12
	v_mov_b32_e32 v11, v12
	v_mov_b32_e32 v16, v12
	v_mov_b32_e32 v17, v12
	v_mov_b32_e32 v18, v12
	v_mov_b32_e32 v19, v12
	v_mov_b32_e32 v20, v12
	v_mov_b32_e32 v21, v12
	v_mov_b32_e32 v22, v12
	v_mov_b32_e32 v23, v12
	v_mov_b32_e32 v28, v12
	v_mov_b32_e32 v29, v12
	v_mov_b32_e32 v30, v12
	v_mov_b32_e32 v31, v12
	v_mov_b32_e32 v32, v12
	v_mov_b32_e32 v33, v12
	v_mov_b32_e32 v34, v12
	v_mov_b32_e32 v35, v12
	v_mov_b32_e32 v36, v12
	v_mov_b32_e32 v37, v12
	v_mov_b32_e32 v38, v12
	v_mov_b32_e32 v39, v12
	v_mov_b32_e32 v40, v12
	v_mov_b32_e32 v41, v12
	v_mov_b32_e32 v42, v12
	v_mov_b32_e32 v43, v12
	v_mov_b32_e32 v44, v12
	v_mov_b32_e32 v45, v12
	v_mov_b32_e32 v46, v12
	v_mov_b32_e32 v47, v12
	v_mov_b32_e32 v48, v12
	v_mov_b32_e32 v49, v12
	v_mov_b32_e32 v50, v12
	v_mov_b32_e32 v51, v12
	v_mov_b32_e32 v52, v12
	v_mov_b32_e32 v53, v12
	v_mov_b32_e32 v54, v12
	v_mov_b32_e32 v55, v12
	v_mov_b32_e32 v56, v12
	v_mov_b32_e32 v57, v12
	v_mov_b32_e32 v58, v12
	v_mov_b32_e32 v59, v12
	v_mov_b32_e32 v60, v12
	v_mov_b32_e32 v61, v12
	v_mov_b32_e32 v62, v12
	v_mov_b32_e32 v63, v12
	v_mov_b32_e32 v64, v12
	v_mov_b32_e32 v65, v12
	v_mov_b32_e32 v66, v12
	v_mov_b32_e32 v67, v12
	v_mov_b32_e32 v68, v12
	v_mov_b32_e32 v69, v12
	v_mov_b32_e32 v70, v12
	v_mov_b32_e32 v71, v12
	v_mov_b32_e32 v72, v12
	v_mov_b32_e32 v73, v12
	v_mov_b32_e32 v74, v12
	v_mov_b32_e32 v75, v12
	v_mov_b32_e32 v76, v12
	v_mov_b32_e32 v77, v12
	v_mov_b32_e32 v78, v12
	v_mov_b32_e32 v79, v12
	v_mov_b32_e32 v80, v12
	v_mov_b32_e32 v81, v12
	v_mov_b32_e32 v82, v12
	v_mov_b32_e32 v83, v12
	v_mov_b32_e32 v84, v12
	v_mov_b32_e32 v85, v12
	v_mov_b32_e32 v86, v12
	v_mov_b32_e32 v87, v12
	v_mov_b32_e32 v88, v12
	v_mov_b32_e32 v89, v12
	v_mov_b32_e32 v90, v12
	v_mov_b32_e32 v91, v12
	v_mov_b32_e32 v92, v12
	v_mov_b32_e32 v93, v12
	v_mov_b32_e32 v94, v12
	v_mov_b32_e32 v95, v12
	v_mov_b32_e32 v96, v12
	v_mov_b32_e32 v97, v12
	v_mov_b32_e32 v98, v12
	v_mov_b32_e32 v99, v12
	v_mov_b32_e32 v100, v12
	v_mov_b32_e32 v101, v12
	v_mov_b32_e32 v102, v12
	v_mov_b32_e32 v103, v12
	v_mov_b32_e32 v104, v12
	v_mov_b32_e32 v105, v12
	v_mov_b32_e32 v106, v12
	v_mov_b32_e32 v107, v12
	v_mov_b32_e32 v108, v12
	v_mov_b32_e32 v109, v12
	v_mov_b32_e32 v110, v12
	v_mov_b32_e32 v111, v12
	v_mov_b32_e32 v112, v12
	v_mov_b32_e32 v113, v12
	v_mov_b32_e32 v114, v12
	v_mov_b32_e32 v115, v12
	v_mov_b32_e32 v116, v12
	v_mov_b32_e32 v117, v12
	v_mov_b32_e32 v118, v12
	v_mov_b32_e32 v119, v12
	v_mov_b32_e32 v120, v12
	v_mov_b32_e32 v121, v12
	v_mov_b32_e32 v122, v12
	v_mov_b32_e32 v123, v12
	v_mov_b32_e32 v124, v12
	v_mov_b32_e32 v125, v12
	v_mov_b32_e32 v126, v12
	v_mov_b32_e32 v127, v12
	s_waitcnt vmcnt(0) lgkmcnt(0)
	s_barrier
	v_add3_u32 v141, v136, v138, v139
	v_add3_u32 v210, v137, v138, v139
	v_add3_u32 v180, v136, v138, v140
	v_add3_u32 v211, v137, v138, v140
	v_readfirstlane_b32 s59, v135
	ds_read_b128 v[142:145], v141
	ds_read_b128 v[146:149], v141 offset:2048
	ds_read_b128 v[150:153], v141 offset:4096
	ds_read_b128 v[154:157], v141 offset:6144
	ds_read_b128 v[174:177], v210 offset:32768
	ds_read_b128 v[182:185], v210 offset:34816
	ds_read_b128 v[186:189], v210 offset:36864
	ds_read_b128 v[190:193], v210 offset:38912
	s_mov_b32 s49, 0
	s_mov_b64 s[50:51], s[34:35]
	v_subrev_u32_e32 v178, s34, v130
	v_subrev_u32_e32 v179, s34, v132
	v_xor_b32_e32 v212, 0x10000, v141
	v_xor_b32_e32 v213, 0x10000, v180
	v_xor_b32_e32 v214, 0x10000, v210
	v_xor_b32_e32 v215, 0x10000, v211
	s_add_u32 s59, s59, 0x10000
	s_mov_b32 m0, s59
	s_add_u32 s52, s50, s14
	s_addc_u32 s53, s51, s15
	global_load_lds_dwordx4 v178, s[52:53]
	s_add_u32 m0, s59, 0x2000
	s_add_u32 s52, s50, s16
	s_addc_u32 s53, s51, s17
	global_load_lds_dwordx4 v178, s[52:53]
	s_add_u32 m0, s59, 0x4000
	s_add_u32 s52, s50, s18
	s_addc_u32 s53, s51, s19
	global_load_lds_dwordx4 v178, s[52:53]
	s_add_u32 m0, s59, 0x6000
	s_add_u32 s52, s50, s22
	s_addc_u32 s53, s51, s23
	global_load_lds_dwordx4 v178, s[52:53]
	s_add_u32 m0, s59, 0x8000
	s_add_u32 s52, s50, s40
	s_addc_u32 s53, s51, s41
	global_load_lds_dwordx4 v179, s[52:53]
	s_add_u32 m0, s59, 0xa000
	s_add_u32 s52, s50, s42
	s_addc_u32 s53, s51, s43
	global_load_lds_dwordx4 v179, s[52:53]
	s_add_u32 m0, s59, 0xc000
	s_add_u32 s52, s50, s44
	s_addc_u32 s53, s51, s45
	global_load_lds_dwordx4 v179, s[52:53]
	s_add_u32 m0, s59, 0xe000
	s_add_u32 s52, s50, s46
	s_addc_u32 s53, s51, s47
	global_load_lds_dwordx4 v179, s[52:53]
	s_branch .Lg1_entry

.LBB0_452:
	s_ashr_i32 s46, s60, 3
	s_and_b32 s21, s60, 7
	s_and_b32 s62, s46, -8
	v_mov_b32_e32 v6, v181
	s_or_b32 s46, s62, s21
	s_ashr_i32 s47, s46, 31
	v_lshrrev_b32_e32 v7, 4, v6
	v_lshlrev_b32_e32 v1, 6, v6
	v_xor_b32_e32 v0, v7, v6
	v_and_b32_e32 v8, 0x3c0, v1
	v_lshlrev_b32_e32 v1, 7, v6
	s_and_b32 s20, s55, 7
	s_bfe_u32 s61, s60, 0x30003
	s_lshl_b64 s[48:49], s[46:47], 19
	v_lshlrev_b32_e32 v0, 3, v0
	v_and_b32_e32 v1, 0xfffffc00, v1
	s_add_u32 s48, s3, s48
	v_and_or_b32 v0, v0, 56, v1
	s_addc_u32 s49, s54, s49
	s_lshl_b32 s21, s61, 19
	v_ashrrev_i32_e32 v1, 31, v0
	v_lshl_add_u32 v140, v6, 4, 0
	s_add_u32 s50, s34, s21
	v_lshlrev_b64 v[0:1], 1, v[0:1]
	v_readfirstlane_b32 s21, v140
	v_add_u32_e32 v9, 0x2000, v140
	v_lshl_add_u64 v[2:3], s[48:49], 0, v[0:1]
	s_mov_b32 m0, s21
	v_readfirstlane_b32 s21, v9
	v_add_u32_e32 v9, 0x4000, v140
	s_barrier
	global_load_lds_dwordx4 v[2:3], off
	v_lshl_add_u64 v[4:5], v[2:3], 0, s[6:7]
	s_mov_b32 m0, s21
	v_readfirstlane_b32 s21, v9
	global_load_lds_dwordx4 v[4:5], off
	v_lshl_add_u64 v[4:5], v[2:3], 0, s[8:9]
	s_mov_b32 m0, s21
	v_lshl_add_u64 v[2:3], v[2:3], 0, s[10:11]
	global_load_lds_dwordx4 v[4:5], off
	v_add_u32_e32 v4, 0x6000, v140
	s_addc_u32 s51, s35, 0
	v_readfirstlane_b32 s21, v4
	s_mov_b32 m0, s21
	v_add_u32_e32 v4, 0xa000, v140
	global_load_lds_dwordx4 v[2:3], off
	v_add_u32_e32 v2, 0x8000, v140
	v_lshl_add_u64 v[132:133], s[50:51], 0, v[0:1]
	v_readfirstlane_b32 s21, v2
	s_mov_b32 m0, s21
	v_readfirstlane_b32 s21, v4
	v_add_u32_e32 v4, 0xc000, v140
	global_load_lds_dwordx4 v[132:133], off
	v_lshl_add_u64 v[2:3], v[132:133], 0, s[6:7]
	s_mov_b32 m0, s21
	v_readfirstlane_b32 s21, v4
	v_add_u32_e32 v4, 0xe000, v140
	global_load_lds_dwordx4 v[2:3], off
	v_lshl_add_u64 v[2:3], v[132:133], 0, s[8:9]
	s_mov_b32 m0, s21
	v_readfirstlane_b32 s21, v4
	global_load_lds_dwordx4 v[2:3], off
	v_lshl_add_u64 v[2:3], v[132:133], 0, s[10:11]
	s_mov_b32 m0, s21
	v_ashrrev_i32_e32 v4, 6, v6
	global_load_lds_dwordx4 v[2:3], off
	v_lshrrev_b32_e32 v5, 30, v4
	v_add_u32_e32 v5, v4, v5
	s_or_b32 s48, s62, s20
	v_bfe_u32 v2, v6, 4, 2
	v_bfe_u32 v3, v6, 1, 3
	v_and_b32_e32 v6, 0x7fffc, v5
	s_ashr_i32 s49, s48, 31
	v_sub_u32_e32 v4, v4, v6
	s_lshl_b64 s[48:49], s[48:49], 19
	v_lshlrev_b32_e32 v142, 13, v4
	v_bitop3_b32 v4, v7, v3, 3 bitop3:0x6c
	v_bitop3_b32 v2, v2, v3, 4 bitop3:0x36
	s_add_u32 s48, s34, s48
	v_lshlrev_b32_e32 v5, 12, v5
	v_lshlrev_b32_e32 v4, 3, v4
	v_lshlrev_b32_e32 v2, 3, v2
	s_addc_u32 s49, s35, s49
	v_and_b32_e32 v141, 0xffffc000, v5
	v_lshl_add_u64 v[134:135], s[48:49], 0, v[0:1]
	s_mov_b64 s[48:49], 0
	v_lshlrev_b32_e32 v143, 1, v8
	v_lshlrev_b32_e32 v144, 1, v4
	v_lshlrev_b32_e32 v145, 1, v2
	s_mov_b32 s62, 0
	s_mov_b32 s47, 0
	v_mov_b32_e32 v40, 0
	v_mov_b32_e32 v41, v129
	v_mov_b32_e32 v42, v129
	v_mov_b32_e32 v43, v129
	v_mov_b32_e32 v48, 0
	v_mov_b32_e32 v49, v129
	v_mov_b32_e32 v50, v129
	v_mov_b32_e32 v51, v129
	v_mov_b32_e32 v0, 0
	v_mov_b32_e32 v1, v129
	v_mov_b32_e32 v2, v129
	v_mov_b32_e32 v3, v129
	v_mov_b32_e32 v4, 0
	v_mov_b32_e32 v5, v129
	v_mov_b32_e32 v6, v129
	v_mov_b32_e32 v7, v129
	v_mov_b32_e32 v8, 0
	v_mov_b32_e32 v9, v129
	v_mov_b32_e32 v10, v129
	v_mov_b32_e32 v11, v129
	v_mov_b32_e32 v12, 0
	v_mov_b32_e32 v13, v129
	v_mov_b32_e32 v14, v129
	v_mov_b32_e32 v15, v129
	v_mov_b32_e32 v16, 0
	v_mov_b32_e32 v17, v129
	v_mov_b32_e32 v18, v129
	v_mov_b32_e32 v19, v129
	v_mov_b32_e32 v20, 0
	v_mov_b32_e32 v21, v129
	v_mov_b32_e32 v22, v129
	v_mov_b32_e32 v23, v129
	v_mov_b32_e32 v24, 0
	v_mov_b32_e32 v25, v129
	v_mov_b32_e32 v26, v129
	v_mov_b32_e32 v27, v129
	v_mov_b32_e32 v28, 0
	v_mov_b32_e32 v29, v129
	v_mov_b32_e32 v30, v129
	v_mov_b32_e32 v31, v129
	v_mov_b32_e32 v32, 0
	v_mov_b32_e32 v33, v129
	v_mov_b32_e32 v34, v129
	v_mov_b32_e32 v35, v129
	v_mov_b32_e32 v36, 0
	v_mov_b32_e32 v37, v129
	v_mov_b32_e32 v38, v129
	v_mov_b32_e32 v39, v129
	v_mov_b32_e32 v44, 0
	v_mov_b32_e32 v45, v129
	v_mov_b32_e32 v46, v129
	v_mov_b32_e32 v47, v129
	v_mov_b32_e32 v52, 0
	v_mov_b32_e32 v53, v129
	v_mov_b32_e32 v54, v129
	v_mov_b32_e32 v55, v129
	v_mov_b32_e32 v56, 0
	v_mov_b32_e32 v57, v129
	v_mov_b32_e32 v58, v129
	v_mov_b32_e32 v59, v129
	v_mov_b32_e32 v60, 0
	v_mov_b32_e32 v61, v129
	v_mov_b32_e32 v62, v129
	v_mov_b32_e32 v63, v129
	v_mov_b32_e32 v64, 0
	v_mov_b32_e32 v65, v129
	v_mov_b32_e32 v66, v129
	v_mov_b32_e32 v67, v129
	v_mov_b32_e32 v68, 0
	v_mov_b32_e32 v69, v129
	v_mov_b32_e32 v70, v129
	v_mov_b32_e32 v71, v129
	v_mov_b32_e32 v72, 0
	v_mov_b32_e32 v73, v129
	v_mov_b32_e32 v74, v129
	v_mov_b32_e32 v75, v129
	v_mov_b32_e32 v76, 0
	v_mov_b32_e32 v77, v129
	v_mov_b32_e32 v78, v129
	v_mov_b32_e32 v79, v129
	v_mov_b32_e32 v80, 0
	v_mov_b32_e32 v81, v129
	v_mov_b32_e32 v82, v129
	v_mov_b32_e32 v83, v129
	v_mov_b32_e32 v84, 0
	v_mov_b32_e32 v85, v129
	v_mov_b32_e32 v86, v129
	v_mov_b32_e32 v87, v129
	v_mov_b32_e32 v88, 0
	v_mov_b32_e32 v89, v129
	v_mov_b32_e32 v90, v129
	v_mov_b32_e32 v91, v129
	v_mov_b32_e32 v92, 0
	v_mov_b32_e32 v93, v129
	v_mov_b32_e32 v94, v129
	v_mov_b32_e32 v95, v129
	v_mov_b32_e32 v96, 0
	v_mov_b32_e32 v97, v129
	v_mov_b32_e32 v98, v129
	v_mov_b32_e32 v99, v129
	v_mov_b32_e32 v100, 0
	v_mov_b32_e32 v101, v129
	v_mov_b32_e32 v102, v129
	v_mov_b32_e32 v103, v129
	v_mov_b32_e32 v104, 0
	v_mov_b32_e32 v105, v129
	v_mov_b32_e32 v106, v129
	v_mov_b32_e32 v107, v129
	v_mov_b32_e32 v108, 0
	v_mov_b32_e32 v109, v129
	v_mov_b32_e32 v110, v129
	v_mov_b32_e32 v111, v129
	v_mov_b32_e32 v112, 0
	v_mov_b32_e32 v113, v129
	v_mov_b32_e32 v114, v129
	v_mov_b32_e32 v115, v129
	v_mov_b32_e32 v116, 0
	v_mov_b32_e32 v117, v129
	v_mov_b32_e32 v118, v129
	v_mov_b32_e32 v119, v129
	v_mov_b32_e32 v120, 0
	v_mov_b32_e32 v121, v129
	v_mov_b32_e32 v122, v129
	v_mov_b32_e32 v123, v129
	v_mov_b32_e32 v124, 0
	v_mov_b32_e32 v125, v129
	v_mov_b32_e32 v126, v129
	v_mov_b32_e32 v127, v129
	s_waitcnt vmcnt(0) lgkmcnt(0)
	s_barrier
	v_add3_u32 v180, v141, v143, v144
	v_add3_u32 v215, v142, v143, v144
	v_add3_u32 v214, v141, v143, v145
	v_add3_u32 v216, v142, v143, v145
	v_readfirstlane_b32 s62, v140
	ds_read_b128 v[146:149], v180
	ds_read_b128 v[150:153], v180 offset:2048
	ds_read_b128 v[154:157], v180 offset:4096
	ds_read_b128 v[158:161], v180 offset:6144
	ds_read_b128 v[182:185], v215 offset:32768
	ds_read_b128 v[186:189], v215 offset:34816
	ds_read_b128 v[190:193], v215 offset:36864
	ds_read_b128 v[194:197], v215 offset:38912
	s_mov_b32 s47, 0
	s_mov_b64 s[48:49], s[34:35]
	v_subrev_u32_e32 v178, s34, v134
	v_subrev_u32_e32 v179, s34, v132
	v_xor_b32_e32 v217, 0x10000, v180
	v_xor_b32_e32 v218, 0x10000, v214
	v_xor_b32_e32 v219, 0x10000, v215
	v_xor_b32_e32 v220, 0x10000, v216
	s_add_u32 s62, s62, 0x10000
	s_mov_b32 m0, s62
	s_add_u32 s50, s48, s12
	s_addc_u32 s51, s49, s13
	global_load_lds_dwordx4 v178, s[50:51]
	s_add_u32 m0, s62, 0x2000
	s_add_u32 s50, s48, s14
	s_addc_u32 s51, s49, s15
	global_load_lds_dwordx4 v178, s[50:51]
	s_add_u32 m0, s62, 0x4000
	s_add_u32 s50, s48, s16
	s_addc_u32 s51, s49, s17
	global_load_lds_dwordx4 v178, s[50:51]
	s_add_u32 m0, s62, 0x6000
	s_add_u32 s50, s48, s18
	s_addc_u32 s51, s49, s19
	global_load_lds_dwordx4 v178, s[50:51]
	s_add_u32 m0, s62, 0x8000
	s_add_u32 s50, s48, s22
	s_addc_u32 s51, s49, s23
	global_load_lds_dwordx4 v179, s[50:51]
	s_add_u32 m0, s62, 0xa000
	s_add_u32 s50, s48, s36
	s_addc_u32 s51, s49, s37
	global_load_lds_dwordx4 v179, s[50:51]
	s_add_u32 m0, s62, 0xc000
	s_add_u32 s50, s48, s40
	s_addc_u32 s51, s49, s41
	global_load_lds_dwordx4 v179, s[50:51]
	s_add_u32 m0, s62, 0xe000
	s_add_u32 s50, s48, s42
	s_addc_u32 s51, s49, s43
	global_load_lds_dwordx4 v179, s[50:51]
	s_branch .Lg2_entry

.LBB0_660:
	s_ashr_i32 s96, s94, 3
	s_and_b32 s21, s94, 7
	s_and_b32 s70, s96, -8
	s_or_b32 s64, s70, s21
	s_lshl_b32 s20, s91, 11
	s_ashr_i32 s65, s64, 31
	v_mov_b32_e32 v6, v181
	s_and_b32 s97, s93, 7
	s_bfe_u32 s6, s91, 0x30008
	s_and_b32 s20, s20, 0x380000
	s_lshl_b64 s[66:67], s[64:65], 19
	s_add_u32 s66, s3, s66
	v_lshrrev_b32_e32 v7, 4, v6
	v_lshlrev_b32_e32 v1, 6, v6
	v_xor_b32_e32 v0, v7, v6
	v_and_b32_e32 v8, 0x3c0, v1
	v_lshlrev_b32_e32 v1, 7, v6
	s_addc_u32 s67, s72, s67
	s_lshl_b32 s21, s94, 5
	v_lshlrev_b32_e32 v0, 3, v0
	v_and_b32_e32 v1, 0xfffffc00, v1
	s_and_b32 s95, s21, 0x700
	v_and_or_b32 v0, v0, 56, v1
	s_lshl_b32 s21, s95, 11
	v_ashrrev_i32_e32 v1, 31, v0
	v_lshl_add_u32 v142, v6, 4, 0
	s_add_u32 s68, s73, s21
	v_lshlrev_b64 v[0:1], 1, v[0:1]
	v_readfirstlane_b32 s21, v142
	v_add_u32_e32 v9, 0x2000, v142
	v_lshl_add_u64 v[2:3], s[66:67], 0, v[0:1]
	s_mov_b32 m0, s21
	v_readfirstlane_b32 s21, v9
	v_add_u32_e32 v9, 0x4000, v142
	s_waitcnt vmcnt(63) expcnt(7) lgkmcnt(15)
	s_barrier
	global_load_lds_dwordx4 v[2:3], off
	v_lshl_add_u64 v[4:5], v[2:3], 0, s[8:9]
	s_mov_b32 m0, s21
	v_readfirstlane_b32 s21, v9
	global_load_lds_dwordx4 v[4:5], off
	v_lshl_add_u64 v[4:5], v[2:3], 0, s[10:11]
	s_mov_b32 m0, s21
	s_addc_u32 s69, s74, 0
	global_load_lds_dwordx4 v[4:5], off
	v_add_u32_e32 v4, 0x6000, v142
	v_lshl_add_u64 v[2:3], v[2:3], 0, s[12:13]
	v_readfirstlane_b32 s21, v4
	v_add_u32_e32 v4, 0x8000, v142
	s_mov_b32 m0, s21
	v_readfirstlane_b32 s21, v4
	v_add_u32_e32 v9, 0xa000, v142
	global_load_lds_dwordx4 v[2:3], off
	v_lshl_add_u64 v[2:3], s[68:69], 0, v[0:1]
	s_mov_b32 m0, s21
	v_readfirstlane_b32 s21, v9
	v_add_u32_e32 v9, 0xc000, v142
	global_load_lds_dwordx4 v[2:3], off
	v_lshl_add_u64 v[4:5], v[2:3], 0, s[8:9]
	s_mov_b32 m0, s21
	v_readfirstlane_b32 s21, v9
	global_load_lds_dwordx4 v[4:5], off
	v_lshl_add_u64 v[4:5], v[2:3], 0, s[10:11]
	s_mov_b32 m0, s21
	v_lshl_add_u64 v[2:3], v[2:3], 0, s[12:13]
	global_load_lds_dwordx4 v[4:5], off
	v_add_u32_e32 v4, 0xe000, v142
	s_or_b32 s66, s70, s97
	v_readfirstlane_b32 s21, v4
	s_mov_b32 m0, s21
	v_ashrrev_i32_e32 v4, 6, v6
	global_load_lds_dwordx4 v[2:3], off
	v_lshrrev_b32_e32 v5, 30, v4
	s_ashr_i32 s67, s66, 31
	v_add_u32_e32 v5, v4, v5
	s_lshl_b64 s[68:69], s[66:67], 19
	v_bfe_u32 v2, v6, 4, 2
	v_bfe_u32 v3, v6, 1, 3
	v_and_b32_e32 v6, 0x7fffc, v5
	s_add_u32 s68, s34, s68
	v_sub_u32_e32 v4, v4, v6
	s_addc_u32 s69, s35, s69
	v_lshlrev_b32_e32 v144, 13, v4
	v_bitop3_b32 v4, v7, v3, 3 bitop3:0x6c
	v_bitop3_b32 v2, v2, v3, 4 bitop3:0x36
	v_lshl_add_u64 v[138:139], s[68:69], 0, v[0:1]
	s_add_u32 s68, s34, s20
	v_lshlrev_b32_e32 v5, 12, v5
	v_lshlrev_b32_e32 v4, 3, v4
	v_lshlrev_b32_e32 v2, 3, v2
	s_addc_u32 s69, s35, 0
	v_and_b32_e32 v143, 0xffffc000, v5
	v_lshl_add_u64 v[140:141], s[68:69], 0, v[0:1]
	s_mov_b64 s[68:69], 0
	v_lshlrev_b32_e32 v145, 1, v8
	v_lshlrev_b32_e32 v174, 1, v4
	v_lshlrev_b32_e32 v175, 1, v2
	s_mov_b32 vcc_lo, 0
	s_mov_b32 s86, 0
	v_mov_b32_e32 v4, 0
	v_mov_b32_e32 v5, v131
	v_mov_b32_e32 v6, v131
	v_mov_b32_e32 v7, v131
	v_mov_b32_e32 v12, 0
	v_mov_b32_e32 v13, v131
	v_mov_b32_e32 v14, v131
	v_mov_b32_e32 v15, v131
	v_mov_b32_e32 v0, 0
	v_mov_b32_e32 v1, v131
	v_mov_b32_e32 v2, v131
	v_mov_b32_e32 v3, v131
	v_mov_b32_e32 v8, 0
	v_mov_b32_e32 v9, v131
	v_mov_b32_e32 v10, v131
	v_mov_b32_e32 v11, v131
	v_mov_b32_e32 v16, 0
	v_mov_b32_e32 v17, v131
	v_mov_b32_e32 v18, v131
	v_mov_b32_e32 v19, v131
	v_mov_b32_e32 v20, 0
	v_mov_b32_e32 v21, v131
	v_mov_b32_e32 v22, v131
	v_mov_b32_e32 v23, v131
	v_mov_b32_e32 v24, 0
	v_mov_b32_e32 v25, v131
	v_mov_b32_e32 v26, v131
	v_mov_b32_e32 v27, v131
	v_mov_b32_e32 v28, 0
	v_mov_b32_e32 v29, v131
	v_mov_b32_e32 v30, v131
	v_mov_b32_e32 v31, v131
	v_mov_b32_e32 v32, 0
	v_mov_b32_e32 v33, v131
	v_mov_b32_e32 v34, v131
	v_mov_b32_e32 v35, v131
	v_mov_b32_e32 v36, 0
	v_mov_b32_e32 v37, v131
	v_mov_b32_e32 v38, v131
	v_mov_b32_e32 v39, v131
	v_mov_b32_e32 v40, 0
	v_mov_b32_e32 v41, v131
	v_mov_b32_e32 v42, v131
	v_mov_b32_e32 v43, v131
	v_mov_b32_e32 v44, 0
	v_mov_b32_e32 v45, v131
	v_mov_b32_e32 v46, v131
	v_mov_b32_e32 v47, v131
	v_mov_b32_e32 v48, 0
	v_mov_b32_e32 v49, v131
	v_mov_b32_e32 v50, v131
	v_mov_b32_e32 v51, v131
	v_mov_b32_e32 v52, 0
	v_mov_b32_e32 v53, v131
	v_mov_b32_e32 v54, v131
	v_mov_b32_e32 v55, v131
	v_mov_b32_e32 v56, 0
	v_mov_b32_e32 v57, v131
	v_mov_b32_e32 v58, v131
	v_mov_b32_e32 v59, v131
	v_mov_b32_e32 v60, 0
	v_mov_b32_e32 v61, v131
	v_mov_b32_e32 v62, v131
	v_mov_b32_e32 v63, v131
	v_mov_b32_e32 v64, 0
	v_mov_b32_e32 v65, v131
	v_mov_b32_e32 v66, v131
	v_mov_b32_e32 v67, v131
	v_mov_b32_e32 v68, 0
	v_mov_b32_e32 v69, v131
	v_mov_b32_e32 v70, v131
	v_mov_b32_e32 v71, v131
	v_mov_b32_e32 v72, 0
	v_mov_b32_e32 v73, v131
	v_mov_b32_e32 v74, v131
	v_mov_b32_e32 v75, v131
	v_mov_b32_e32 v76, 0
	v_mov_b32_e32 v77, v131
	v_mov_b32_e32 v78, v131
	v_mov_b32_e32 v79, v131
	v_mov_b32_e32 v80, 0
	v_mov_b32_e32 v81, v131
	v_mov_b32_e32 v82, v131
	v_mov_b32_e32 v83, v131
	v_mov_b32_e32 v84, 0
	v_mov_b32_e32 v85, v131
	v_mov_b32_e32 v86, v131
	v_mov_b32_e32 v87, v131
	v_mov_b32_e32 v88, 0
	v_mov_b32_e32 v89, v131
	v_mov_b32_e32 v90, v131
	v_mov_b32_e32 v91, v131
	v_mov_b32_e32 v92, 0
	v_mov_b32_e32 v93, v131
	v_mov_b32_e32 v94, v131
	v_mov_b32_e32 v95, v131
	v_mov_b32_e32 v96, 0
	v_mov_b32_e32 v97, v131
	v_mov_b32_e32 v98, v131
	v_mov_b32_e32 v99, v131
	v_mov_b32_e32 v100, 0
	v_mov_b32_e32 v101, v131
	v_mov_b32_e32 v102, v131
	v_mov_b32_e32 v103, v131
	v_mov_b32_e32 v104, 0
	v_mov_b32_e32 v105, v131
	v_mov_b32_e32 v106, v131
	v_mov_b32_e32 v107, v131
	v_mov_b32_e32 v108, 0
	v_mov_b32_e32 v109, v131
	v_mov_b32_e32 v110, v131
	v_mov_b32_e32 v111, v131
	v_mov_b32_e32 v112, 0
	v_mov_b32_e32 v113, v131
	v_mov_b32_e32 v114, v131
	v_mov_b32_e32 v115, v131
	v_mov_b32_e32 v116, 0
	v_mov_b32_e32 v117, v131
	v_mov_b32_e32 v118, v131
	v_mov_b32_e32 v119, v131
	v_mov_b32_e32 v120, 0
	v_mov_b32_e32 v121, v131
	v_mov_b32_e32 v122, v131
	v_mov_b32_e32 v123, v131
	v_mov_b32_e32 v124, 0
	v_mov_b32_e32 v125, v131
	v_mov_b32_e32 v126, v131
	v_mov_b32_e32 v127, v131
	s_waitcnt vmcnt(0) lgkmcnt(0)
	s_barrier
	v_add3_u32 v180, v143, v145, v174
	v_add3_u32 v245, v144, v145, v174
	v_add3_u32 v244, v143, v145, v175
	v_add3_u32 v246, v144, v145, v175
	v_readfirstlane_b32 s87, v142
	ds_read_b128 v[176:179], v180
	ds_read_b128 v[182:185], v180 offset:2048
	ds_read_b128 v[186:189], v180 offset:4096
	ds_read_b128 v[190:193], v180 offset:6144
	ds_read_b128 v[210:213], v245 offset:32768
	ds_read_b128 v[214:217], v245 offset:34816
	ds_read_b128 v[218:221], v245 offset:36864
	ds_read_b128 v[222:225], v245 offset:38912
	s_mov_b32 s86, 0
	s_mov_b64 s[68:69], s[34:35]
	v_subrev_u32_e32 v242, s34, v138
	v_subrev_u32_e32 v243, s34, v140
	v_xor_b32_e32 v247, 0x10000, v180
	v_xor_b32_e32 v248, 0x10000, v244
	v_xor_b32_e32 v249, 0x10000, v245
	v_xor_b32_e32 v250, 0x10000, v246
	s_add_u32 s87, s87, 0x10000
	s_mov_b32 m0, s87
	s_add_u32 s70, s68, 0x4000080
	s_addc_u32 s71, s69, 0
	global_load_lds_dwordx4 v242, s[70:71]
	s_add_u32 m0, s87, 0x2000
	s_add_u32 s70, s68, 0x4020080
	s_addc_u32 s71, s69, 0
	global_load_lds_dwordx4 v242, s[70:71]
	s_add_u32 m0, s87, 0x4000
	s_add_u32 s70, s68, 0x4040080
	s_addc_u32 s71, s69, 0
	global_load_lds_dwordx4 v242, s[70:71]
	s_add_u32 m0, s87, 0x6000
	s_add_u32 s70, s68, s14
	s_addc_u32 s71, s69, s15
	global_load_lds_dwordx4 v242, s[70:71]
	s_add_u32 m0, s87, 0x8000
	s_add_u32 s70, s68, s16
	s_addc_u32 s71, s69, s17
	global_load_lds_dwordx4 v243, s[70:71]
	s_add_u32 m0, s87, 0xa000
	s_add_u32 s70, s68, s18
	s_addc_u32 s71, s69, s19
	global_load_lds_dwordx4 v243, s[70:71]
	s_add_u32 m0, s87, 0xc000
	s_add_u32 s70, s68, s22
	s_addc_u32 s71, s69, s23
	global_load_lds_dwordx4 v243, s[70:71]
	s_add_u32 m0, s87, 0xe000
	s_add_u32 s70, s68, s36
	s_addc_u32 s71, s69, s37
	global_load_lds_dwordx4 v243, s[70:71]
	s_branch .Lg5_entry

.LBB0_667:
	ds_read_b128 v[2:5], v0
	v_lshl_add_u64 v[6:7], v[138:139], 0, s[68:69]
	v_add_co_u32_e32 v8, vcc, 0x6000000, v6
	s_add_u32 s68, s68, 0x20000
	s_nop 0
	v_addc_co_u32_e32 v9, vcc, 0, v7, vcc
	s_waitcnt lgkmcnt(0)
	global_store_dwordx4 v[8:9], v[2:5], off sc1
	ds_read_b128 v[2:5], v0 offset:1152
	v_add_co_u32_e32 v8, vcc, 0x6008000, v6
	s_addc_u32 s69, s69, 0
	s_nop 0
	v_addc_co_u32_e32 v9, vcc, 0, v7, vcc
	s_waitcnt lgkmcnt(0)
	global_store_dwordx4 v[8:9], v[2:5], off sc1
	ds_read_b128 v[2:5], v0 offset:2304
	v_add_co_u32_e32 v8, vcc, 0x6010000, v6
	s_cmp_lg_u32 s68, 0x80000
	s_nop 0
	v_addc_co_u32_e32 v9, vcc, 0, v7, vcc
	s_waitcnt lgkmcnt(0)
	global_store_dwordx4 v[8:9], v[2:5], off sc1
	ds_read_b128 v[2:5], v0 offset:3456
	v_add_co_u32_e32 v6, vcc, 0x6018000, v6
	v_add_u32_e32 v0, 0x1200, v0
	s_nop 0
	v_addc_co_u32_e32 v7, vcc, 0, v7, vcc
	s_waitcnt lgkmcnt(0)
	global_store_dwordx4 v[6:7], v[2:5], off sc1
	s_cbranch_scc1 .LBB0_667
	v_mov_b32_e32 v6, v181
	s_waitcnt lgkmcnt(0)
	s_lshl_b32 s68, s6, 20
	v_lshrrev_b32_e32 v7, 4, v6
	v_lshlrev_b32_e32 v1, 6, v6
	v_xor_b32_e32 v0, v7, v6
	v_and_b32_e32 v8, 0x3c0, v1
	v_lshlrev_b32_e32 v1, 8, v6
	v_lshlrev_b32_e32 v0, 3, v0
	v_and_b32_e32 v1, 0xfffff800, v1
	s_lshl_b64 s[20:21], s[64:65], 20
	v_and_or_b32 v0, v0, 56, v1
	s_add_u32 s20, s75, s20
	v_ashrrev_i32_e32 v1, 31, v0
	s_addc_u32 s21, s88, s21
	v_lshlrev_b64 v[0:1], 1, v[0:1]
	v_lshl_add_u32 v174, v6, 4, 0
	v_lshl_add_u64 v[2:3], s[20:21], 0, v[0:1]
	v_readfirstlane_b32 s20, v174
	v_add_u32_e32 v9, 0x2000, v174
	s_mov_b32 m0, s20
	v_readfirstlane_b32 s20, v9
	v_add_u32_e32 v9, 0x4000, v174
	s_barrier
	global_load_lds_dwordx4 v[2:3], off
	v_lshl_add_u64 v[4:5], v[2:3], 0, s[10:11]
	s_mov_b32 m0, s20
	v_readfirstlane_b32 s20, v9
	global_load_lds_dwordx4 v[4:5], off
	v_lshl_add_u64 v[4:5], v[2:3], 0, s[40:41]
	s_mov_b32 m0, s20
	s_lshl_b32 s64, s95, 12
	global_load_lds_dwordx4 v[4:5], off
	v_add_u32_e32 v4, 0x6000, v174
	s_add_u32 s64, s89, s64
	v_readfirstlane_b32 s20, v4
	v_add_u32_e32 v4, 0x8000, v174
	s_addc_u32 s65, s90, 0
	v_lshl_add_u64 v[2:3], v[2:3], 0, s[42:43]
	s_mov_b32 m0, s20
	v_readfirstlane_b32 s20, v4
	v_add_u32_e32 v9, 0xa000, v174
	global_load_lds_dwordx4 v[2:3], off
	v_lshl_add_u64 v[2:3], s[64:65], 0, v[0:1]
	s_mov_b32 m0, s20
	v_readfirstlane_b32 s20, v9
	v_add_u32_e32 v9, 0xc000, v174
	global_load_lds_dwordx4 v[2:3], off
	v_lshl_add_u64 v[4:5], v[2:3], 0, s[10:11]
	s_mov_b32 m0, s20
	v_readfirstlane_b32 s20, v9
	global_load_lds_dwordx4 v[4:5], off
	v_lshl_add_u64 v[4:5], v[2:3], 0, s[40:41]
	s_mov_b32 m0, s20
	v_lshl_add_u64 v[2:3], v[2:3], 0, s[42:43]
	global_load_lds_dwordx4 v[4:5], off
	v_add_u32_e32 v4, 0xe000, v174
	s_mov_b32 s69, 0
	v_readfirstlane_b32 s20, v4
	s_mov_b32 m0, s20
	v_ashrrev_i32_e32 v4, 6, v6
	global_load_lds_dwordx4 v[2:3], off
	v_lshrrev_b32_e32 v5, 30, v4
	v_add_u32_e32 v5, v4, v5
	s_lshl_b64 s[20:21], s[66:67], 20
	v_bfe_u32 v2, v6, 4, 2
	v_bfe_u32 v3, v6, 1, 3
	v_and_b32_e32 v6, 0x7fffc, v5
	s_add_u32 s20, s34, s20
	v_sub_u32_e32 v4, v4, v6
	s_addc_u32 s21, s35, s21
	v_lshlrev_b32_e32 v5, 12, v5
	v_lshlrev_b32_e32 v176, 13, v4
	v_bitop3_b32 v4, v7, v3, 3 bitop3:0x6c
	v_bitop3_b32 v2, v2, v3, 4 bitop3:0x36
	v_lshl_add_u64 v[142:143], s[20:21], 0, v[0:1]
	s_add_u32 s20, s34, s68
	v_and_b32_e32 v175, 0xffffc000, v5
	v_lshlrev_b32_e32 v5, 3, v4
	v_lshlrev_b32_e32 v2, 3, v2
	s_addc_u32 s21, s35, 0
	v_mov_b32_e32 v4, 0
	v_lshl_add_u64 v[144:145], s[20:21], 0, v[0:1]
	s_mov_b64 s[64:65], 0
	v_lshlrev_b32_e32 v177, 1, v8
	v_lshlrev_b32_e32 v178, 1, v5
	v_lshlrev_b32_e32 v179, 1, v2
	s_mov_b32 s68, 0
	v_mov_b32_e32 v5, v4
	v_mov_b32_e32 v6, v4
	v_mov_b32_e32 v7, v4
	v_mov_b32_e32 v8, v4
	v_mov_b32_e32 v9, v4
	v_mov_b32_e32 v10, v4
	v_mov_b32_e32 v11, v4
	v_mov_b32_e32 v0, v4
	v_mov_b32_e32 v1, v4
	v_mov_b32_e32 v2, v4
	v_mov_b32_e32 v3, v4
	v_mov_b32_e32 v12, v4
	v_mov_b32_e32 v13, v4
	v_mov_b32_e32 v14, v4
	v_mov_b32_e32 v15, v4
	v_mov_b32_e32 v16, v4
	v_mov_b32_e32 v17, v4
	v_mov_b32_e32 v18, v4
	v_mov_b32_e32 v19, v4
	v_mov_b32_e32 v20, v4
	v_mov_b32_e32 v21, v4
	v_mov_b32_e32 v22, v4
	v_mov_b32_e32 v23, v4
	v_mov_b32_e32 v24, v4
	v_mov_b32_e32 v25, v4
	v_mov_b32_e32 v26, v4
	v_mov_b32_e32 v27, v4
	v_mov_b32_e32 v28, v4
	v_mov_b32_e32 v29, v4
	v_mov_b32_e32 v30, v4
	v_mov_b32_e32 v31, v4
	v_mov_b32_e32 v32, v4
	v_mov_b32_e32 v33, v4
	v_mov_b32_e32 v34, v4
	v_mov_b32_e32 v35, v4
	v_mov_b32_e32 v36, v4
	v_mov_b32_e32 v37, v4
	v_mov_b32_e32 v38, v4
	v_mov_b32_e32 v39, v4
	v_mov_b32_e32 v40, v4
	v_mov_b32_e32 v41, v4
	v_mov_b32_e32 v42, v4
	v_mov_b32_e32 v43, v4
	v_mov_b32_e32 v44, v4
	v_mov_b32_e32 v45, v4
	v_mov_b32_e32 v46, v4
	v_mov_b32_e32 v47, v4
	v_mov_b32_e32 v48, v4
	v_mov_b32_e32 v49, v4
	v_mov_b32_e32 v50, v4
	v_mov_b32_e32 v51, v4
	v_mov_b32_e32 v52, v4
	v_mov_b32_e32 v53, v4
	v_mov_b32_e32 v54, v4
	v_mov_b32_e32 v55, v4
	v_mov_b32_e32 v56, v4
	v_mov_b32_e32 v57, v4
	v_mov_b32_e32 v58, v4
	v_mov_b32_e32 v59, v4
	v_mov_b32_e32 v60, v4
	v_mov_b32_e32 v61, v4
	v_mov_b32_e32 v62, v4
	v_mov_b32_e32 v63, v4
	v_mov_b32_e32 v64, v4
	v_mov_b32_e32 v65, v4
	v_mov_b32_e32 v66, v4
	v_mov_b32_e32 v67, v4
	v_mov_b32_e32 v68, v4
	v_mov_b32_e32 v69, v4
	v_mov_b32_e32 v70, v4
	v_mov_b32_e32 v71, v4
	v_mov_b32_e32 v72, v4
	v_mov_b32_e32 v73, v4
	v_mov_b32_e32 v74, v4
	v_mov_b32_e32 v75, v4
	v_mov_b32_e32 v76, v4
	v_mov_b32_e32 v77, v4
	v_mov_b32_e32 v78, v4
	v_mov_b32_e32 v79, v4
	v_mov_b32_e32 v80, v4
	v_mov_b32_e32 v81, v4
	v_mov_b32_e32 v82, v4
	v_mov_b32_e32 v83, v4
	v_mov_b32_e32 v84, v4
	v_mov_b32_e32 v85, v4
	v_mov_b32_e32 v86, v4
	v_mov_b32_e32 v87, v4
	v_mov_b32_e32 v88, v4
	v_mov_b32_e32 v89, v4
	v_mov_b32_e32 v90, v4
	v_mov_b32_e32 v91, v4
	v_mov_b32_e32 v92, v4
	v_mov_b32_e32 v93, v4
	v_mov_b32_e32 v94, v4
	v_mov_b32_e32 v95, v4
	v_mov_b32_e32 v96, v4
	v_mov_b32_e32 v97, v4
	v_mov_b32_e32 v98, v4
	v_mov_b32_e32 v99, v4
	v_mov_b32_e32 v100, v4
	v_mov_b32_e32 v101, v4
	v_mov_b32_e32 v102, v4
	v_mov_b32_e32 v103, v4
	v_mov_b32_e32 v104, v4
	v_mov_b32_e32 v105, v4
	v_mov_b32_e32 v106, v4
	v_mov_b32_e32 v107, v4
	v_mov_b32_e32 v108, v4
	v_mov_b32_e32 v109, v4
	v_mov_b32_e32 v110, v4
	v_mov_b32_e32 v111, v4
	v_mov_b32_e32 v112, v4
	v_mov_b32_e32 v113, v4
	v_mov_b32_e32 v114, v4
	v_mov_b32_e32 v115, v4
	v_mov_b32_e32 v116, v4
	v_mov_b32_e32 v117, v4
	v_mov_b32_e32 v118, v4
	v_mov_b32_e32 v119, v4
	v_mov_b32_e32 v120, v4
	v_mov_b32_e32 v121, v4
	v_mov_b32_e32 v122, v4
	v_mov_b32_e32 v123, v4
	v_mov_b32_e32 v124, v4
	v_mov_b32_e32 v125, v4
	v_mov_b32_e32 v126, v4
	v_mov_b32_e32 v127, v4
	s_waitcnt vmcnt(0) lgkmcnt(0)
	s_barrier
	v_add3_u32 v180, v175, v177, v178
	v_add3_u32 v249, v176, v177, v178
	v_add3_u32 v248, v175, v177, v179
	v_add3_u32 v250, v176, v177, v179
	v_readfirstlane_b32 s69, v174
	ds_read_b128 v[182:185], v180
	ds_read_b128 v[186:189], v180 offset:2048
	ds_read_b128 v[190:193], v180 offset:4096
	ds_read_b128 v[194:197], v180 offset:6144
	ds_read_b128 v[214:217], v249 offset:32768
	ds_read_b128 v[218:221], v249 offset:34816
	ds_read_b128 v[222:225], v249 offset:36864
	ds_read_b128 v[226:229], v249 offset:38912
	s_mov_b32 s68, 0
	s_mov_b64 s[64:65], s[34:35]
	v_subrev_u32_e32 v246, s34, v142
	v_subrev_u32_e32 v247, s34, v144
	v_xor_b32_e32 v142, 0x10000, v180
	v_xor_b32_e32 v143, 0x10000, v248
	v_xor_b32_e32 v144, 0x10000, v249
	v_xor_b32_e32 v145, 0x10000, v250
	s_add_u32 s69, s69, 0x10000
	s_mov_b32 m0, s69
	s_add_u32 s66, s64, s44
	s_addc_u32 s67, s65, s45
	global_load_lds_dwordx4 v246, s[66:67]
	s_add_u32 m0, s69, 0x2000
	s_add_u32 s66, s64, s46
	s_addc_u32 s67, s65, s47
	global_load_lds_dwordx4 v246, s[66:67]
	s_add_u32 m0, s69, 0x4000
	s_add_u32 s66, s64, s48
	s_addc_u32 s67, s65, s49
	global_load_lds_dwordx4 v246, s[66:67]
	s_add_u32 m0, s69, 0x6000
	s_add_u32 s66, s64, s50
	s_addc_u32 s67, s65, s51
	global_load_lds_dwordx4 v246, s[66:67]
	s_add_u32 m0, s69, 0x8000
	s_add_u32 s66, s64, s52
	s_addc_u32 s67, s65, s53
	global_load_lds_dwordx4 v247, s[66:67]
	s_add_u32 m0, s69, 0xa000
	s_add_u32 s66, s64, s54
	s_addc_u32 s67, s65, s55
	global_load_lds_dwordx4 v247, s[66:67]
	s_add_u32 m0, s69, 0xc000
	s_add_u32 s66, s64, s60
	s_addc_u32 s67, s65, s61
	global_load_lds_dwordx4 v247, s[66:67]
	s_add_u32 m0, s69, 0xe000
	s_add_u32 s66, s64, s62
	s_addc_u32 s67, s65, s63
	global_load_lds_dwordx4 v247, s[66:67]
	s_branch .Lg6_entry
.Lg6_top:
	s_waitcnt lgkmcnt(0)
	s_waitcnt vmcnt(0)
	s_barrier
	s_xor_b32 s69, s69, 0x10000
	ds_read_b128 v[182:185], v180
	ds_read_b128 v[186:189], v180 offset:2048
	ds_read_b128 v[190:193], v180 offset:4096
	ds_read_b128 v[194:197], v180 offset:6144
	ds_read_b128 v[214:217], v249 offset:32768
	ds_read_b128 v[218:221], v249 offset:34816
	ds_read_b128 v[222:225], v249 offset:36864
	ds_read_b128 v[226:229], v249 offset:38912
	v_mfma_f32_16x16x32_bf16 v[60:63], v[198:201], v[230:233], v[60:63]
	v_mfma_f32_16x16x32_bf16 v[56:59], v[198:201], v[234:237], v[56:59]
	s_mov_b32 m0, s69
	s_add_u32 s66, s64, s44
	s_addc_u32 s67, s65, s45
	global_load_lds_dwordx4 v246, s[66:67]
	v_mfma_f32_16x16x32_bf16 v[52:55], v[198:201], v[238:241], v[52:55]
	v_mfma_f32_16x16x32_bf16 v[48:51], v[198:201], v[242:245], v[48:51]
	s_add_u32 m0, s69, 0x2000
	s_add_u32 s66, s64, s46
	s_addc_u32 s67, s65, s47
	global_load_lds_dwordx4 v246, s[66:67]
	v_mfma_f32_16x16x32_bf16 v[44:47], v[202:205], v[230:233], v[44:47]
	v_mfma_f32_16x16x32_bf16 v[40:43], v[202:205], v[234:237], v[40:43]
	s_add_u32 m0, s69, 0x4000
	s_add_u32 s66, s64, s48
	s_addc_u32 s67, s65, s49
	global_load_lds_dwordx4 v246, s[66:67]
	v_mfma_f32_16x16x32_bf16 v[36:39], v[202:205], v[238:241], v[36:39]
	v_mfma_f32_16x16x32_bf16 v[32:35], v[202:205], v[242:245], v[32:35]
	s_add_u32 m0, s69, 0x6000
	s_add_u32 s66, s64, s50
	s_addc_u32 s67, s65, s51
	global_load_lds_dwordx4 v246, s[66:67]
	v_mfma_f32_16x16x32_bf16 v[28:31], v[206:209], v[230:233], v[28:31]
	v_mfma_f32_16x16x32_bf16 v[24:27], v[206:209], v[234:237], v[24:27]
	s_add_u32 m0, s69, 0x8000
	s_add_u32 s66, s64, s52
	s_addc_u32 s67, s65, s53
	global_load_lds_dwordx4 v247, s[66:67]
	v_mfma_f32_16x16x32_bf16 v[20:23], v[206:209], v[238:241], v[20:23]
	v_mfma_f32_16x16x32_bf16 v[16:19], v[206:209], v[242:245], v[16:19]
	s_add_u32 m0, s69, 0xa000
	s_add_u32 s66, s64, s54
	s_addc_u32 s67, s65, s55
	global_load_lds_dwordx4 v247, s[66:67]
	v_mfma_f32_16x16x32_bf16 v[12:15], v[210:213], v[230:233], v[12:15]
	v_mfma_f32_16x16x32_bf16 v[0:3], v[210:213], v[234:237], v[0:3]
	s_add_u32 m0, s69, 0xc000
	s_add_u32 s66, s64, s60
	s_addc_u32 s67, s65, s61
	global_load_lds_dwordx4 v247, s[66:67]
	v_mfma_f32_16x16x32_bf16 v[8:11], v[210:213], v[238:241], v[8:11]
	v_mfma_f32_16x16x32_bf16 v[4:7], v[210:213], v[242:245], v[4:7]
	s_add_u32 m0, s69, 0xe000
	s_add_u32 s66, s64, s62
	s_addc_u32 s67, s65, s63
	global_load_lds_dwordx4 v247, s[66:67]
.Lg6_entry:
	ds_read_b128 v[198:201], v180 offset:8192
	ds_read_b128 v[202:205], v180 offset:10240
	ds_read_b128 v[206:209], v180 offset:12288
	ds_read_b128 v[210:213], v180 offset:14336
	s_waitcnt lgkmcnt(4)
	v_mfma_f32_16x16x32_bf16 v[124:127], v[182:185], v[214:217], v[124:127]
	v_mfma_f32_16x16x32_bf16 v[120:123], v[182:185], v[218:221], v[120:123]
	v_mfma_f32_16x16x32_bf16 v[116:119], v[182:185], v[222:225], v[116:119]
	v_mfma_f32_16x16x32_bf16 v[112:115], v[182:185], v[226:229], v[112:115]
	v_mfma_f32_16x16x32_bf16 v[108:111], v[186:189], v[214:217], v[108:111]
	v_mfma_f32_16x16x32_bf16 v[104:107], v[186:189], v[218:221], v[104:107]
	v_mfma_f32_16x16x32_bf16 v[100:103], v[186:189], v[222:225], v[100:103]
	v_mfma_f32_16x16x32_bf16 v[96:99], v[186:189], v[226:229], v[96:99]
	v_mfma_f32_16x16x32_bf16 v[92:95], v[190:193], v[214:217], v[92:95]
	v_mfma_f32_16x16x32_bf16 v[88:91], v[190:193], v[218:221], v[88:91]
	v_mfma_f32_16x16x32_bf16 v[84:87], v[190:193], v[222:225], v[84:87]
	v_mfma_f32_16x16x32_bf16 v[80:83], v[190:193], v[226:229], v[80:83]
	v_mfma_f32_16x16x32_bf16 v[76:79], v[194:197], v[214:217], v[76:79]
	v_mfma_f32_16x16x32_bf16 v[72:75], v[194:197], v[218:221], v[72:75]
	v_mfma_f32_16x16x32_bf16 v[68:71], v[194:197], v[222:225], v[68:71]
	v_mfma_f32_16x16x32_bf16 v[64:67], v[194:197], v[226:229], v[64:67]
	ds_read_b128 v[182:185], v248
	ds_read_b128 v[186:189], v248 offset:2048
	ds_read_b128 v[190:193], v248 offset:4096
	ds_read_b128 v[194:197], v248 offset:6144
	ds_read_b128 v[230:233], v250 offset:32768
	ds_read_b128 v[234:237], v250 offset:34816
	ds_read_b128 v[238:241], v250 offset:36864
	ds_read_b128 v[242:245], v250 offset:38912
	s_waitcnt lgkmcnt(8)
	v_mfma_f32_16x16x32_bf16 v[60:63], v[198:201], v[214:217], v[60:63]
	v_mfma_f32_16x16x32_bf16 v[56:59], v[198:201], v[218:221], v[56:59]
	v_mfma_f32_16x16x32_bf16 v[52:55], v[198:201], v[222:225], v[52:55]
	v_mfma_f32_16x16x32_bf16 v[48:51], v[198:201], v[226:229], v[48:51]
	v_mfma_f32_16x16x32_bf16 v[44:47], v[202:205], v[214:217], v[44:47]
	v_mfma_f32_16x16x32_bf16 v[40:43], v[202:205], v[218:221], v[40:43]
	v_mfma_f32_16x16x32_bf16 v[36:39], v[202:205], v[222:225], v[36:39]
	v_mfma_f32_16x16x32_bf16 v[32:35], v[202:205], v[226:229], v[32:35]
	v_mfma_f32_16x16x32_bf16 v[28:31], v[206:209], v[214:217], v[28:31]
	v_mfma_f32_16x16x32_bf16 v[24:27], v[206:209], v[218:221], v[24:27]
	v_mfma_f32_16x16x32_bf16 v[20:23], v[206:209], v[222:225], v[20:23]
	v_mfma_f32_16x16x32_bf16 v[16:19], v[206:209], v[226:229], v[16:19]
	v_mfma_f32_16x16x32_bf16 v[12:15], v[210:213], v[214:217], v[12:15]
	v_mfma_f32_16x16x32_bf16 v[0:3], v[210:213], v[218:221], v[0:3]
	v_mfma_f32_16x16x32_bf16 v[8:11], v[210:213], v[222:225], v[8:11]
	v_mfma_f32_16x16x32_bf16 v[4:7], v[210:213], v[226:229], v[4:7]
	ds_read_b128 v[198:201], v248 offset:8192
	ds_read_b128 v[202:205], v248 offset:10240
	ds_read_b128 v[206:209], v248 offset:12288
	ds_read_b128 v[210:213], v248 offset:14336
	s_waitcnt lgkmcnt(4)
	v_mfma_f32_16x16x32_bf16 v[124:127], v[182:185], v[230:233], v[124:127]
	v_mfma_f32_16x16x32_bf16 v[120:123], v[182:185], v[234:237], v[120:123]
	v_mfma_f32_16x16x32_bf16 v[116:119], v[182:185], v[238:241], v[116:119]
	v_mfma_f32_16x16x32_bf16 v[112:115], v[182:185], v[242:245], v[112:115]
	v_mfma_f32_16x16x32_bf16 v[108:111], v[186:189], v[230:233], v[108:111]
	v_mfma_f32_16x16x32_bf16 v[104:107], v[186:189], v[234:237], v[104:107]
	v_mfma_f32_16x16x32_bf16 v[100:103], v[186:189], v[238:241], v[100:103]
	v_mfma_f32_16x16x32_bf16 v[96:99], v[186:189], v[242:245], v[96:99]
	v_mfma_f32_16x16x32_bf16 v[92:95], v[190:193], v[230:233], v[92:95]
	v_mfma_f32_16x16x32_bf16 v[88:91], v[190:193], v[234:237], v[88:91]
	v_mfma_f32_16x16x32_bf16 v[84:87], v[190:193], v[238:241], v[84:87]
	v_mfma_f32_16x16x32_bf16 v[80:83], v[190:193], v[242:245], v[80:83]
	v_mfma_f32_16x16x32_bf16 v[76:79], v[194:197], v[230:233], v[76:79]
	v_mfma_f32_16x16x32_bf16 v[72:75], v[194:197], v[234:237], v[72:75]
	v_mfma_f32_16x16x32_bf16 v[68:71], v[194:197], v[238:241], v[68:71]
	v_mfma_f32_16x16x32_bf16 v[64:67], v[194:197], v[242:245], v[64:67]
	s_add_u32 s64, s64, 0x80
	s_addc_u32 s65, s65, 0
	s_add_i32 s68, s68, 1
	s_cmp_lt_u32 s68, 31
	s_cbranch_scc0 .Lg6_last
	s_waitcnt lgkmcnt(0)
	s_waitcnt vmcnt(0)
	s_barrier
	s_xor_b32 s69, s69, 0x10000
	ds_read_b128 v[182:185], v142
	ds_read_b128 v[186:189], v142 offset:2048
	ds_read_b128 v[190:193], v142 offset:4096
	ds_read_b128 v[194:197], v142 offset:6144
	ds_read_b128 v[214:217], v144 offset:32768
	ds_read_b128 v[218:221], v144 offset:34816
	ds_read_b128 v[222:225], v144 offset:36864
	ds_read_b128 v[226:229], v144 offset:38912
	v_mfma_f32_16x16x32_bf16 v[60:63], v[198:201], v[230:233], v[60:63]
	v_mfma_f32_16x16x32_bf16 v[56:59], v[198:201], v[234:237], v[56:59]
	s_mov_b32 m0, s69
	s_add_u32 s66, s64, s44
	s_addc_u32 s67, s65, s45
	global_load_lds_dwordx4 v246, s[66:67]
	v_mfma_f32_16x16x32_bf16 v[52:55], v[198:201], v[238:241], v[52:55]
	v_mfma_f32_16x16x32_bf16 v[48:51], v[198:201], v[242:245], v[48:51]
	s_add_u32 m0, s69, 0x2000
	s_add_u32 s66, s64, s46
	s_addc_u32 s67, s65, s47
	global_load_lds_dwordx4 v246, s[66:67]
	v_mfma_f32_16x16x32_bf16 v[44:47], v[202:205], v[230:233], v[44:47]
	v_mfma_f32_16x16x32_bf16 v[40:43], v[202:205], v[234:237], v[40:43]
	s_add_u32 m0, s69, 0x4000
	s_add_u32 s66, s64, s48
	s_addc_u32 s67, s65, s49
	global_load_lds_dwordx4 v246, s[66:67]
	v_mfma_f32_16x16x32_bf16 v[36:39], v[202:205], v[238:241], v[36:39]
	v_mfma_f32_16x16x32_bf16 v[32:35], v[202:205], v[242:245], v[32:35]
	s_add_u32 m0, s69, 0x6000
	s_add_u32 s66, s64, s50
	s_addc_u32 s67, s65, s51
	global_load_lds_dwordx4 v246, s[66:67]
	v_mfma_f32_16x16x32_bf16 v[28:31], v[206:209], v[230:233], v[28:31]
	v_mfma_f32_16x16x32_bf16 v[24:27], v[206:209], v[234:237], v[24:27]
	s_add_u32 m0, s69, 0x8000
	s_add_u32 s66, s64, s52
	s_addc_u32 s67, s65, s53
	global_load_lds_dwordx4 v247, s[66:67]
	v_mfma_f32_16x16x32_bf16 v[20:23], v[206:209], v[238:241], v[20:23]
	v_mfma_f32_16x16x32_bf16 v[16:19], v[206:209], v[242:245], v[16:19]
	s_add_u32 m0, s69, 0xa000
	s_add_u32 s66, s64, s54
	s_addc_u32 s67, s65, s55
	global_load_lds_dwordx4 v247, s[66:67]
	v_mfma_f32_16x16x32_bf16 v[12:15], v[210:213], v[230:233], v[12:15]
	v_mfma_f32_16x16x32_bf16 v[0:3], v[210:213], v[234:237], v[0:3]
	s_add_u32 m0, s69, 0xc000
	s_add_u32 s66, s64, s60
	s_addc_u32 s67, s65, s61
	global_load_lds_dwordx4 v247, s[66:67]
	v_mfma_f32_16x16x32_bf16 v[8:11], v[210:213], v[238:241], v[8:11]
	v_mfma_f32_16x16x32_bf16 v[4:7], v[210:213], v[242:245], v[4:7]
	s_add_u32 m0, s69, 0xe000
	s_add_u32 s66, s64, s62
	s_addc_u32 s67, s65, s63
	global_load_lds_dwordx4 v247, s[66:67]
	ds_read_b128 v[198:201], v142 offset:8192
	ds_read_b128 v[202:205], v142 offset:10240
	ds_read_b128 v[206:209], v142 offset:12288
	ds_read_b128 v[210:213], v142 offset:14336
	s_waitcnt lgkmcnt(4)
	v_mfma_f32_16x16x32_bf16 v[124:127], v[182:185], v[214:217], v[124:127]
	v_mfma_f32_16x16x32_bf16 v[120:123], v[182:185], v[218:221], v[120:123]
	v_mfma_f32_16x16x32_bf16 v[116:119], v[182:185], v[222:225], v[116:119]
	v_mfma_f32_16x16x32_bf16 v[112:115], v[182:185], v[226:229], v[112:115]
	v_mfma_f32_16x16x32_bf16 v[108:111], v[186:189], v[214:217], v[108:111]
	v_mfma_f32_16x16x32_bf16 v[104:107], v[186:189], v[218:221], v[104:107]
	v_mfma_f32_16x16x32_bf16 v[100:103], v[186:189], v[222:225], v[100:103]
	v_mfma_f32_16x16x32_bf16 v[96:99], v[186:189], v[226:229], v[96:99]
	v_mfma_f32_16x16x32_bf16 v[92:95], v[190:193], v[214:217], v[92:95]
	v_mfma_f32_16x16x32_bf16 v[88:91], v[190:193], v[218:221], v[88:91]
	v_mfma_f32_16x16x32_bf16 v[84:87], v[190:193], v[222:225], v[84:87]
	v_mfma_f32_16x16x32_bf16 v[80:83], v[190:193], v[226:229], v[80:83]
	v_mfma_f32_16x16x32_bf16 v[76:79], v[194:197], v[214:217], v[76:79]
	v_mfma_f32_16x16x32_bf16 v[72:75], v[194:197], v[218:221], v[72:75]
	v_mfma_f32_16x16x32_bf16 v[68:71], v[194:197], v[222:225], v[68:71]
	v_mfma_f32_16x16x32_bf16 v[64:67], v[194:197], v[226:229], v[64:67]
	ds_read_b128 v[182:185], v143
	ds_read_b128 v[186:189], v143 offset:2048
	ds_read_b128 v[190:193], v143 offset:4096
	ds_read_b128 v[194:197], v143 offset:6144
	ds_read_b128 v[230:233], v145 offset:32768
	ds_read_b128 v[234:237], v145 offset:34816
	ds_read_b128 v[238:241], v145 offset:36864
	ds_read_b128 v[242:245], v145 offset:38912
	s_waitcnt lgkmcnt(8)
	v_mfma_f32_16x16x32_bf16 v[60:63], v[198:201], v[214:217], v[60:63]
	v_mfma_f32_16x16x32_bf16 v[56:59], v[198:201], v[218:221], v[56:59]
	v_mfma_f32_16x16x32_bf16 v[52:55], v[198:201], v[222:225], v[52:55]
	v_mfma_f32_16x16x32_bf16 v[48:51], v[198:201], v[226:229], v[48:51]
	v_mfma_f32_16x16x32_bf16 v[44:47], v[202:205], v[214:217], v[44:47]
	v_mfma_f32_16x16x32_bf16 v[40:43], v[202:205], v[218:221], v[40:43]
	v_mfma_f32_16x16x32_bf16 v[36:39], v[202:205], v[222:225], v[36:39]
	v_mfma_f32_16x16x32_bf16 v[32:35], v[202:205], v[226:229], v[32:35]
	v_mfma_f32_16x16x32_bf16 v[28:31], v[206:209], v[214:217], v[28:31]
	v_mfma_f32_16x16x32_bf16 v[24:27], v[206:209], v[218:221], v[24:27]
	v_mfma_f32_16x16x32_bf16 v[20:23], v[206:209], v[222:225], v[20:23]
	v_mfma_f32_16x16x32_bf16 v[16:19], v[206:209], v[226:229], v[16:19]
	v_mfma_f32_16x16x32_bf16 v[12:15], v[210:213], v[214:217], v[12:15]
	v_mfma_f32_16x16x32_bf16 v[0:3], v[210:213], v[218:221], v[0:3]
	v_mfma_f32_16x16x32_bf16 v[8:11], v[210:213], v[222:225], v[8:11]
	v_mfma_f32_16x16x32_bf16 v[4:7], v[210:213], v[226:229], v[4:7]
	ds_read_b128 v[198:201], v143 offset:8192
	ds_read_b128 v[202:205], v143 offset:10240
	ds_read_b128 v[206:209], v143 offset:12288
	ds_read_b128 v[210:213], v143 offset:14336
	s_waitcnt lgkmcnt(4)
	v_mfma_f32_16x16x32_bf16 v[124:127], v[182:185], v[230:233], v[124:127]
	v_mfma_f32_16x16x32_bf16 v[120:123], v[182:185], v[234:237], v[120:123]
	v_mfma_f32_16x16x32_bf16 v[116:119], v[182:185], v[238:241], v[116:119]
	v_mfma_f32_16x16x32_bf16 v[112:115], v[182:185], v[242:245], v[112:115]
	v_mfma_f32_16x16x32_bf16 v[108:111], v[186:189], v[230:233], v[108:111]
	v_mfma_f32_16x16x32_bf16 v[104:107], v[186:189], v[234:237], v[104:107]
	v_mfma_f32_16x16x32_bf16 v[100:103], v[186:189], v[238:241], v[100:103]
	v_mfma_f32_16x16x32_bf16 v[96:99], v[186:189], v[242:245], v[96:99]
	v_mfma_f32_16x16x32_bf16 v[92:95], v[190:193], v[230:233], v[92:95]
	v_mfma_f32_16x16x32_bf16 v[88:91], v[190:193], v[234:237], v[88:91]
	v_mfma_f32_16x16x32_bf16 v[84:87], v[190:193], v[238:241], v[84:87]
	v_mfma_f32_16x16x32_bf16 v[80:83], v[190:193], v[242:245], v[80:83]
	v_mfma_f32_16x16x32_bf16 v[76:79], v[194:197], v[230:233], v[76:79]
	v_mfma_f32_16x16x32_bf16 v[72:75], v[194:197], v[234:237], v[72:75]
	v_mfma_f32_16x16x32_bf16 v[68:71], v[194:197], v[238:241], v[68:71]
	v_mfma_f32_16x16x32_bf16 v[64:67], v[194:197], v[242:245], v[64:67]
	s_add_u32 s64, s64, 0x80
	s_addc_u32 s65, s65, 0
	s_add_i32 s68, s68, 1
	s_branch .Lg6_top
.Lg6_last:
	s_waitcnt lgkmcnt(0)
	s_waitcnt vmcnt(0)
	s_barrier
	s_xor_b32 s69, s69, 0x10000
	ds_read_b128 v[182:185], v142
	ds_read_b128 v[186:189], v142 offset:2048
	ds_read_b128 v[190:193], v142 offset:4096
	ds_read_b128 v[194:197], v142 offset:6144
	ds_read_b128 v[214:217], v144 offset:32768
	ds_read_b128 v[218:221], v144 offset:34816
	ds_read_b128 v[222:225], v144 offset:36864
	ds_read_b128 v[226:229], v144 offset:38912
	v_mfma_f32_16x16x32_bf16 v[60:63], v[198:201], v[230:233], v[60:63]
	v_mfma_f32_16x16x32_bf16 v[56:59], v[198:201], v[234:237], v[56:59]
	v_mfma_f32_16x16x32_bf16 v[52:55], v[198:201], v[238:241], v[52:55]
	v_mfma_f32_16x16x32_bf16 v[48:51], v[198:201], v[242:245], v[48:51]
	v_mfma_f32_16x16x32_bf16 v[44:47], v[202:205], v[230:233], v[44:47]
	v_mfma_f32_16x16x32_bf16 v[40:43], v[202:205], v[234:237], v[40:43]
	v_mfma_f32_16x16x32_bf16 v[36:39], v[202:205], v[238:241], v[36:39]
	v_mfma_f32_16x16x32_bf16 v[32:35], v[202:205], v[242:245], v[32:35]
	v_mfma_f32_16x16x32_bf16 v[28:31], v[206:209], v[230:233], v[28:31]
	v_mfma_f32_16x16x32_bf16 v[24:27], v[206:209], v[234:237], v[24:27]
	v_mfma_f32_16x16x32_bf16 v[20:23], v[206:209], v[238:241], v[20:23]
	v_mfma_f32_16x16x32_bf16 v[16:19], v[206:209], v[242:245], v[16:19]
	v_mfma_f32_16x16x32_bf16 v[12:15], v[210:213], v[230:233], v[12:15]
	v_mfma_f32_16x16x32_bf16 v[0:3], v[210:213], v[234:237], v[0:3]
	v_mfma_f32_16x16x32_bf16 v[8:11], v[210:213], v[238:241], v[8:11]
	v_mfma_f32_16x16x32_bf16 v[4:7], v[210:213], v[242:245], v[4:7]
	ds_read_b128 v[198:201], v142 offset:8192
	ds_read_b128 v[202:205], v142 offset:10240
	ds_read_b128 v[206:209], v142 offset:12288
	ds_read_b128 v[210:213], v142 offset:14336
	s_waitcnt lgkmcnt(4)
	v_mfma_f32_16x16x32_bf16 v[124:127], v[182:185], v[214:217], v[124:127]
	v_mfma_f32_16x16x32_bf16 v[120:123], v[182:185], v[218:221], v[120:123]
	v_mfma_f32_16x16x32_bf16 v[116:119], v[182:185], v[222:225], v[116:119]
	v_mfma_f32_16x16x32_bf16 v[112:115], v[182:185], v[226:229], v[112:115]
	v_mfma_f32_16x16x32_bf16 v[108:111], v[186:189], v[214:217], v[108:111]
	v_mfma_f32_16x16x32_bf16 v[104:107], v[186:189], v[218:221], v[104:107]
	v_mfma_f32_16x16x32_bf16 v[100:103], v[186:189], v[222:225], v[100:103]
	v_mfma_f32_16x16x32_bf16 v[96:99], v[186:189], v[226:229], v[96:99]
	v_mfma_f32_16x16x32_bf16 v[92:95], v[190:193], v[214:217], v[92:95]
	v_mfma_f32_16x16x32_bf16 v[88:91], v[190:193], v[218:221], v[88:91]
	v_mfma_f32_16x16x32_bf16 v[84:87], v[190:193], v[222:225], v[84:87]
	v_mfma_f32_16x16x32_bf16 v[80:83], v[190:193], v[226:229], v[80:83]
	v_mfma_f32_16x16x32_bf16 v[76:79], v[194:197], v[214:217], v[76:79]
	v_mfma_f32_16x16x32_bf16 v[72:75], v[194:197], v[218:221], v[72:75]
	v_mfma_f32_16x16x32_bf16 v[68:71], v[194:197], v[222:225], v[68:71]
	v_mfma_f32_16x16x32_bf16 v[64:67], v[194:197], v[226:229], v[64:67]
	ds_read_b128 v[182:185], v143
	ds_read_b128 v[186:189], v143 offset:2048
	ds_read_b128 v[190:193], v143 offset:4096
	ds_read_b128 v[194:197], v143 offset:6144
	ds_read_b128 v[230:233], v145 offset:32768
	ds_read_b128 v[234:237], v145 offset:34816
	ds_read_b128 v[238:241], v145 offset:36864
	ds_read_b128 v[242:245], v145 offset:38912
	s_waitcnt lgkmcnt(8)
	v_mfma_f32_16x16x32_bf16 v[60:63], v[198:201], v[214:217], v[60:63]
	v_mfma_f32_16x16x32_bf16 v[56:59], v[198:201], v[218:221], v[56:59]
	v_mfma_f32_16x16x32_bf16 v[52:55], v[198:201], v[222:225], v[52:55]
	v_mfma_f32_16x16x32_bf16 v[48:51], v[198:201], v[226:229], v[48:51]
	v_mfma_f32_16x16x32_bf16 v[44:47], v[202:205], v[214:217], v[44:47]
	v_mfma_f32_16x16x32_bf16 v[40:43], v[202:205], v[218:221], v[40:43]
	v_mfma_f32_16x16x32_bf16 v[36:39], v[202:205], v[222:225], v[36:39]
	v_mfma_f32_16x16x32_bf16 v[32:35], v[202:205], v[226:229], v[32:35]
	v_mfma_f32_16x16x32_bf16 v[28:31], v[206:209], v[214:217], v[28:31]
	v_mfma_f32_16x16x32_bf16 v[24:27], v[206:209], v[218:221], v[24:27]
	v_mfma_f32_16x16x32_bf16 v[20:23], v[206:209], v[222:225], v[20:23]
	v_mfma_f32_16x16x32_bf16 v[16:19], v[206:209], v[226:229], v[16:19]
	v_mfma_f32_16x16x32_bf16 v[12:15], v[210:213], v[214:217], v[12:15]
	v_mfma_f32_16x16x32_bf16 v[0:3], v[210:213], v[218:221], v[0:3]
	v_mfma_f32_16x16x32_bf16 v[8:11], v[210:213], v[222:225], v[8:11]
	v_mfma_f32_16x16x32_bf16 v[4:7], v[210:213], v[226:229], v[4:7]
	ds_read_b128 v[198:201], v143 offset:8192
	ds_read_b128 v[202:205], v143 offset:10240
	ds_read_b128 v[206:209], v143 offset:12288
	ds_read_b128 v[210:213], v143 offset:14336
	s_waitcnt lgkmcnt(4)
	v_mfma_f32_16x16x32_bf16 v[124:127], v[182:185], v[230:233], v[124:127]
	v_mfma_f32_16x16x32_bf16 v[120:123], v[182:185], v[234:237], v[120:123]
	v_mfma_f32_16x16x32_bf16 v[116:119], v[182:185], v[238:241], v[116:119]
	v_mfma_f32_16x16x32_bf16 v[112:115], v[182:185], v[242:245], v[112:115]
	v_mfma_f32_16x16x32_bf16 v[108:111], v[186:189], v[230:233], v[108:111]
	v_mfma_f32_16x16x32_bf16 v[104:107], v[186:189], v[234:237], v[104:107]
	v_mfma_f32_16x16x32_bf16 v[100:103], v[186:189], v[238:241], v[100:103]
	v_mfma_f32_16x16x32_bf16 v[96:99], v[186:189], v[242:245], v[96:99]
	v_mfma_f32_16x16x32_bf16 v[92:95], v[190:193], v[230:233], v[92:95]
	v_mfma_f32_16x16x32_bf16 v[88:91], v[190:193], v[234:237], v[88:91]
	v_mfma_f32_16x16x32_bf16 v[84:87], v[190:193], v[238:241], v[84:87]
	v_mfma_f32_16x16x32_bf16 v[80:83], v[190:193], v[242:245], v[80:83]
	v_mfma_f32_16x16x32_bf16 v[76:79], v[194:197], v[230:233], v[76:79]
	v_mfma_f32_16x16x32_bf16 v[72:75], v[194:197], v[234:237], v[72:75]
	v_mfma_f32_16x16x32_bf16 v[68:71], v[194:197], v[238:241], v[68:71]
	v_mfma_f32_16x16x32_bf16 v[64:67], v[194:197], v[242:245], v[64:67]
	s_add_u32 s64, s64, 0x80
	s_addc_u32 s65, s65, 0
	s_add_i32 s68, s68, 1
	s_waitcnt lgkmcnt(0)
	s_waitcnt vmcnt(0)
	s_barrier
	v_mfma_f32_16x16x32_bf16 v[60:63], v[198:201], v[230:233], v[60:63]
	v_mfma_f32_16x16x32_bf16 v[56:59], v[198:201], v[234:237], v[56:59]
	v_mfma_f32_16x16x32_bf16 v[52:55], v[198:201], v[238:241], v[52:55]
	v_mfma_f32_16x16x32_bf16 v[48:51], v[198:201], v[242:245], v[48:51]
	v_mfma_f32_16x16x32_bf16 v[44:47], v[202:205], v[230:233], v[44:47]
	v_mfma_f32_16x16x32_bf16 v[40:43], v[202:205], v[234:237], v[40:43]
	v_mfma_f32_16x16x32_bf16 v[36:39], v[202:205], v[238:241], v[36:39]
	v_mfma_f32_16x16x32_bf16 v[32:35], v[202:205], v[242:245], v[32:35]
	v_mfma_f32_16x16x32_bf16 v[28:31], v[206:209], v[230:233], v[28:31]
	v_mfma_f32_16x16x32_bf16 v[24:27], v[206:209], v[234:237], v[24:27]
	v_mfma_f32_16x16x32_bf16 v[20:23], v[206:209], v[238:241], v[20:23]
	v_mfma_f32_16x16x32_bf16 v[16:19], v[206:209], v[242:245], v[16:19]
	v_mfma_f32_16x16x32_bf16 v[12:15], v[210:213], v[230:233], v[12:15]
	v_mfma_f32_16x16x32_bf16 v[0:3], v[210:213], v[234:237], v[0:3]
	v_mfma_f32_16x16x32_bf16 v[8:11], v[210:213], v[238:241], v[8:11]
	v_mfma_f32_16x16x32_bf16 v[4:7], v[210:213], v[242:245], v[4:7]
	s_nop 7
	s_nop 7
	s_sub_u32 s64, s64, s34
	s_subb_u32 s65, s65, s35
	s_mov_b32 s69, 0x100000
	s_mov_b32 s70, 0x100000
	s_mov_b64 s[66:67], 0
	s_mov_b64 vcc, exec
	s_branch .LBB0_674

.LBB0_746:
	s_ashr_i32 s20, s60, 2
	v_mov_b32_e32 v6, v181
	s_and_b32 s6, s60, 7
	s_and_b32 s51, s20, -8
	s_or_b32 s46, s51, s6
	v_lshrrev_b32_e32 v7, 4, v6
	v_lshlrev_b32_e32 v1, 6, v6
	v_xor_b32_e32 v0, v7, v6
	v_and_b32_e32 v8, 0x3c0, v1
	v_lshlrev_b32_e32 v1, 8, v6
	s_ashr_i32 s47, s46, 31
	v_lshlrev_b32_e32 v0, 3, v0
	v_and_b32_e32 v1, 0xfffff800, v1
	s_and_b32 s50, s55, 7
	s_bfe_u32 s6, s60, 0x20003
	s_lshl_b64 s[20:21], s[46:47], 20
	v_and_or_b32 v0, v0, 56, v1
	s_add_u32 s20, s3, s20
	v_ashrrev_i32_e32 v1, 31, v0
	s_addc_u32 s21, s52, s21
	v_lshlrev_b64 v[0:1], 1, v[0:1]
	v_lshl_add_u32 v134, v6, 4, 0
	v_lshl_add_u64 v[2:3], s[20:21], 0, v[0:1]
	v_readfirstlane_b32 s20, v134
	v_add_u32_e32 v9, 0x2000, v134
	s_mov_b32 m0, s20
	v_readfirstlane_b32 s20, v9
	v_add_u32_e32 v9, 0x4000, v134
	s_waitcnt vmcnt(63) expcnt(7) lgkmcnt(15)
	s_barrier
	global_load_lds_dwordx4 v[2:3], off
	v_lshl_add_u64 v[4:5], v[2:3], 0, s[8:9]
	s_mov_b32 m0, s20
	v_readfirstlane_b32 s20, v9
	global_load_lds_dwordx4 v[4:5], off
	v_lshl_add_u64 v[4:5], v[2:3], 0, s[10:11]
	s_mov_b32 m0, s20
	s_lshl_b32 s47, s6, 20
	global_load_lds_dwordx4 v[4:5], off
	v_add_u32_e32 v4, 0x6000, v134
	s_add_u32 s48, s53, s47
	v_readfirstlane_b32 s20, v4
	v_add_u32_e32 v4, 0x8000, v134
	s_addc_u32 s49, s54, 0
	v_lshl_add_u64 v[2:3], v[2:3], 0, s[12:13]
	s_mov_b32 m0, s20
	v_readfirstlane_b32 s20, v4
	v_add_u32_e32 v9, 0xa000, v134
	global_load_lds_dwordx4 v[2:3], off
	v_lshl_add_u64 v[2:3], s[48:49], 0, v[0:1]
	s_mov_b32 m0, s20
	v_readfirstlane_b32 s20, v9
	v_add_u32_e32 v9, 0xc000, v134
	global_load_lds_dwordx4 v[2:3], off
	v_lshl_add_u64 v[4:5], v[2:3], 0, s[8:9]
	s_mov_b32 m0, s20
	v_readfirstlane_b32 s20, v9
	global_load_lds_dwordx4 v[4:5], off
	v_lshl_add_u64 v[4:5], v[2:3], 0, s[10:11]
	s_mov_b32 m0, s20
	v_lshl_add_u64 v[2:3], v[2:3], 0, s[12:13]
	global_load_lds_dwordx4 v[4:5], off
	v_add_u32_e32 v4, 0xe000, v134
	v_mov_b32_e32 v36, 0
	v_readfirstlane_b32 s20, v4
	s_mov_b32 m0, s20
	v_ashrrev_i32_e32 v4, 6, v6
	global_load_lds_dwordx4 v[2:3], off
	s_or_b32 s20, s51, s50
	v_lshrrev_b32_e32 v5, 30, v4
	s_ashr_i32 s21, s20, 31
	v_add_u32_e32 v5, v4, v5
	s_lshl_b64 s[20:21], s[20:21], 20
	v_bfe_u32 v2, v6, 4, 2
	v_bfe_u32 v3, v6, 1, 3
	v_and_b32_e32 v6, 0x7fffc, v5
	s_add_u32 s20, s34, s20
	v_sub_u32_e32 v4, v4, v6
	s_addc_u32 s21, s35, s21
	v_lshlrev_b32_e32 v136, 13, v4
	v_bitop3_b32 v4, v7, v3, 3 bitop3:0x6c
	v_bitop3_b32 v2, v2, v3, 4 bitop3:0x36
	v_lshl_add_u64 v[130:131], s[20:21], 0, v[0:1]
	s_add_u32 s20, s34, s47
	v_lshlrev_b32_e32 v5, 12, v5
	v_lshlrev_b32_e32 v4, 3, v4
	v_lshlrev_b32_e32 v2, 3, v2
	s_addc_u32 s21, s35, 0
	v_and_b32_e32 v135, 0xffffc000, v5
	v_lshl_add_u64 v[132:133], s[20:21], 0, v[0:1]
	s_mov_b64 s[48:49], 0
	v_lshlrev_b32_e32 v137, 1, v8
	v_lshlrev_b32_e32 v138, 1, v4
	v_lshlrev_b32_e32 v139, 1, v2
	s_mov_b32 s61, 0
	s_mov_b32 s47, 0
	v_mov_b32_e32 v37, v36
	v_mov_b32_e32 v38, v36
	v_mov_b32_e32 v39, v36
	v_mov_b32_e32 v40, v36
	v_mov_b32_e32 v41, v36
	v_mov_b32_e32 v42, v36
	v_mov_b32_e32 v43, v36
	v_mov_b32_e32 v0, v36
	v_mov_b32_e32 v1, v36
	v_mov_b32_e32 v2, v36
	v_mov_b32_e32 v3, v36
	v_mov_b32_e32 v4, v36
	v_mov_b32_e32 v5, v36
	v_mov_b32_e32 v6, v36
	v_mov_b32_e32 v7, v36
	v_mov_b32_e32 v8, v36
	v_mov_b32_e32 v9, v36
	v_mov_b32_e32 v10, v36
	v_mov_b32_e32 v11, v36
	v_mov_b32_e32 v12, v36
	v_mov_b32_e32 v13, v36
	v_mov_b32_e32 v14, v36
	v_mov_b32_e32 v15, v36
	v_mov_b32_e32 v16, v36
	v_mov_b32_e32 v17, v36
	v_mov_b32_e32 v18, v36
	v_mov_b32_e32 v19, v36
	v_mov_b32_e32 v20, v36
	v_mov_b32_e32 v21, v36
	v_mov_b32_e32 v22, v36
	v_mov_b32_e32 v23, v36
	v_mov_b32_e32 v24, v36
	v_mov_b32_e32 v25, v36
	v_mov_b32_e32 v26, v36
	v_mov_b32_e32 v27, v36
	v_mov_b32_e32 v28, v36
	v_mov_b32_e32 v29, v36
	v_mov_b32_e32 v30, v36
	v_mov_b32_e32 v31, v36
	v_mov_b32_e32 v32, v36
	v_mov_b32_e32 v33, v36
	v_mov_b32_e32 v34, v36
	v_mov_b32_e32 v35, v36
	v_mov_b32_e32 v44, v36
	v_mov_b32_e32 v45, v36
	v_mov_b32_e32 v46, v36
	v_mov_b32_e32 v47, v36
	v_mov_b32_e32 v48, v36
	v_mov_b32_e32 v49, v36
	v_mov_b32_e32 v50, v36
	v_mov_b32_e32 v51, v36
	v_mov_b32_e32 v52, v36
	v_mov_b32_e32 v53, v36
	v_mov_b32_e32 v54, v36
	v_mov_b32_e32 v55, v36
	v_mov_b32_e32 v56, v36
	v_mov_b32_e32 v57, v36
	v_mov_b32_e32 v58, v36
	v_mov_b32_e32 v59, v36
	v_mov_b32_e32 v60, v36
	v_mov_b32_e32 v61, v36
	v_mov_b32_e32 v62, v36
	v_mov_b32_e32 v63, v36
	v_mov_b32_e32 v64, v36
	v_mov_b32_e32 v65, v36
	v_mov_b32_e32 v66, v36
	v_mov_b32_e32 v67, v36
	v_mov_b32_e32 v68, v36
	v_mov_b32_e32 v69, v36
	v_mov_b32_e32 v70, v36
	v_mov_b32_e32 v71, v36
	v_mov_b32_e32 v72, v36
	v_mov_b32_e32 v73, v36
	v_mov_b32_e32 v74, v36
	v_mov_b32_e32 v75, v36
	v_mov_b32_e32 v76, v36
	v_mov_b32_e32 v77, v36
	v_mov_b32_e32 v78, v36
	v_mov_b32_e32 v79, v36
	v_mov_b32_e32 v80, v36
	v_mov_b32_e32 v81, v36
	v_mov_b32_e32 v82, v36
	v_mov_b32_e32 v83, v36
	v_mov_b32_e32 v84, v36
	v_mov_b32_e32 v85, v36
	v_mov_b32_e32 v86, v36
	v_mov_b32_e32 v87, v36
	v_mov_b32_e32 v88, v36
	v_mov_b32_e32 v89, v36
	v_mov_b32_e32 v90, v36
	v_mov_b32_e32 v91, v36
	v_mov_b32_e32 v92, v36
	v_mov_b32_e32 v93, v36
	v_mov_b32_e32 v94, v36
	v_mov_b32_e32 v95, v36
	v_mov_b32_e32 v96, v36
	v_mov_b32_e32 v97, v36
	v_mov_b32_e32 v98, v36
	v_mov_b32_e32 v99, v36
	v_mov_b32_e32 v100, v36
	v_mov_b32_e32 v101, v36
	v_mov_b32_e32 v102, v36
	v_mov_b32_e32 v103, v36
	v_mov_b32_e32 v104, v36
	v_mov_b32_e32 v105, v36
	v_mov_b32_e32 v106, v36
	v_mov_b32_e32 v107, v36
	v_mov_b32_e32 v108, v36
	v_mov_b32_e32 v109, v36
	v_mov_b32_e32 v110, v36
	v_mov_b32_e32 v111, v36
	v_mov_b32_e32 v112, v36
	v_mov_b32_e32 v113, v36
	v_mov_b32_e32 v114, v36
	v_mov_b32_e32 v115, v36
	v_mov_b32_e32 v116, v36
	v_mov_b32_e32 v117, v36
	v_mov_b32_e32 v118, v36
	v_mov_b32_e32 v119, v36
	v_mov_b32_e32 v120, v36
	v_mov_b32_e32 v121, v36
	v_mov_b32_e32 v122, v36
	v_mov_b32_e32 v123, v36
	v_mov_b32_e32 v124, v36
	v_mov_b32_e32 v125, v36
	v_mov_b32_e32 v126, v36
	v_mov_b32_e32 v127, v36
	s_waitcnt vmcnt(0) lgkmcnt(0)
	s_barrier
	v_add3_u32 v141, v135, v137, v138
	v_add3_u32 v210, v136, v137, v138
	v_add3_u32 v180, v135, v137, v139
	v_add3_u32 v211, v136, v137, v139
	v_readfirstlane_b32 s61, v134
	ds_read_b128 v[142:145], v141
	ds_read_b128 v[146:149], v141 offset:2048
	ds_read_b128 v[150:153], v141 offset:4096
	ds_read_b128 v[154:157], v141 offset:6144
	ds_read_b128 v[174:177], v210 offset:32768
	ds_read_b128 v[182:185], v210 offset:34816
	ds_read_b128 v[186:189], v210 offset:36864
	ds_read_b128 v[190:193], v210 offset:38912
	s_mov_b32 s47, 0
	s_mov_b64 s[48:49], s[34:35]
	v_subrev_u32_e32 v178, s34, v130
	v_subrev_u32_e32 v179, s34, v132
	v_xor_b32_e32 v212, 0x10000, v141
	v_xor_b32_e32 v213, 0x10000, v180
	v_xor_b32_e32 v214, 0x10000, v210
	v_xor_b32_e32 v215, 0x10000, v211
	s_add_u32 s61, s61, 0x10000
	s_mov_b32 m0, s61
	s_add_u32 s50, s48, s14
	s_addc_u32 s51, s49, s15
	global_load_lds_dwordx4 v178, s[50:51]
	s_add_u32 m0, s61, 0x2000
	s_add_u32 s50, s48, s16
	s_addc_u32 s51, s49, s17
	global_load_lds_dwordx4 v178, s[50:51]
	s_add_u32 m0, s61, 0x4000
	s_add_u32 s50, s48, s18
	s_addc_u32 s51, s49, s19
	global_load_lds_dwordx4 v178, s[50:51]
	s_add_u32 m0, s61, 0x6000
	s_add_u32 s50, s48, s22
	s_addc_u32 s51, s49, s23
	global_load_lds_dwordx4 v178, s[50:51]
	s_add_u32 m0, s61, 0x8000
	s_add_u32 s50, s48, s36
	s_addc_u32 s51, s49, s37
	global_load_lds_dwordx4 v179, s[50:51]
	s_add_u32 m0, s61, 0xa000
	s_add_u32 s50, s48, s40
	s_addc_u32 s51, s49, s41
	global_load_lds_dwordx4 v179, s[50:51]
	s_add_u32 m0, s61, 0xc000
	s_add_u32 s50, s48, s42
	s_addc_u32 s51, s49, s43
	global_load_lds_dwordx4 v179, s[50:51]
	s_add_u32 m0, s61, 0xe000
	s_add_u32 s50, s48, s44
	s_addc_u32 s51, s49, s45
	global_load_lds_dwordx4 v179, s[50:51]
	s_branch .Lg7_entry

.LBB0_933:
	s_mul_hi_i32 s21, s70, 0x2e8ba2e9
	s_lshr_b32 s56, s21, 31
	s_ashr_i32 s71, s21, 4
	s_add_i32 s71, s71, s56
	s_and_b32 s20, s70, 7
	s_lshl_b32 s62, s71, 3
	s_or_b32 s58, s62, s20
	s_ashr_i32 s20, s70, 3
	s_mul_hi_i32 s21, s20, 0x2e8ba2e9
	v_mov_b32_e32 v6, v181
	s_lshr_b32 s56, s21, 31
	s_ashr_i32 s21, s21, 1
	s_add_i32 s21, s21, s56
	v_lshrrev_b32_e32 v7, 4, v6
	v_lshlrev_b32_e32 v1, 6, v6
	v_xor_b32_e32 v0, v7, v6
	v_and_b32_e32 v8, 0x3c0, v1
	v_lshlrev_b32_e32 v1, 7, v6
	s_mul_i32 s21, s21, 11
	s_ashr_i32 s59, s58, 31
	v_lshlrev_b32_e32 v0, 3, v0
	v_and_b32_e32 v1, 0xfffffc00, v1
	s_and_b32 s64, s69, 7
	s_sub_i32 s56, s20, s21
	s_lshl_b64 s[20:21], s[58:59], 19
	v_and_or_b32 v0, v0, 56, v1
	s_add_u32 s20, s3, s20
	v_ashrrev_i32_e32 v1, 31, v0
	s_addc_u32 s21, s66, s21
	v_lshlrev_b64 v[0:1], 1, v[0:1]
	v_lshl_add_u32 v130, v6, 4, 0
	v_lshl_add_u64 v[2:3], s[20:21], 0, v[0:1]
	v_readfirstlane_b32 s20, v130
	v_add_u32_e32 v9, 0x2000, v130
	s_mov_b32 m0, s20
	v_readfirstlane_b32 s20, v9
	v_add_u32_e32 v9, 0x4000, v130
	s_waitcnt vmcnt(63) expcnt(7) lgkmcnt(15)
	s_barrier
	global_load_lds_dwordx4 v[2:3], off
	v_lshl_add_u64 v[4:5], v[2:3], 0, s[14:15]
	s_mov_b32 m0, s20
	v_readfirstlane_b32 s20, v9
	global_load_lds_dwordx4 v[4:5], off
	v_lshl_add_u64 v[4:5], v[2:3], 0, s[16:17]
	s_mov_b32 m0, s20
	s_ashr_i32 s57, s56, 31
	global_load_lds_dwordx4 v[4:5], off
	v_add_u32_e32 v4, 0x6000, v130
	s_lshl_b64 s[60:61], s[56:57], 19
	v_readfirstlane_b32 s20, v4
	v_lshl_add_u64 v[2:3], v[2:3], 0, s[18:19]
	s_mov_b32 m0, s20
	s_add_u32 s60, s34, s60
	global_load_lds_dwordx4 v[2:3], off
	v_add_u32_e32 v2, 0x8000, v130
	s_addc_u32 s61, s35, s61
	v_readfirstlane_b32 s20, v2
	v_add_u32_e32 v4, 0xa000, v130
	v_lshl_add_u64 v[140:141], s[60:61], 0, v[0:1]
	s_mov_b32 m0, s20
	v_readfirstlane_b32 s20, v4
	v_add_u32_e32 v4, 0xc000, v130
	global_load_lds_dwordx4 v[140:141], off
	v_lshl_add_u64 v[2:3], v[140:141], 0, s[14:15]
	s_mov_b32 m0, s20
	v_readfirstlane_b32 s20, v4
	v_add_u32_e32 v4, 0xe000, v130
	global_load_lds_dwordx4 v[2:3], off
	v_lshl_add_u64 v[2:3], v[140:141], 0, s[16:17]
	s_mov_b32 m0, s20
	v_readfirstlane_b32 s20, v4
	global_load_lds_dwordx4 v[2:3], off
	v_lshl_add_u64 v[2:3], v[140:141], 0, s[18:19]
	s_mov_b32 m0, s20
	v_ashrrev_i32_e32 v4, 6, v6
	global_load_lds_dwordx4 v[2:3], off
	v_lshrrev_b32_e32 v5, 30, v4
	v_add_u32_e32 v5, v4, v5
	s_or_b32 s20, s62, s64
	v_bfe_u32 v2, v6, 4, 2
	v_bfe_u32 v3, v6, 1, 3
	v_and_b32_e32 v6, 0x7fffc, v5
	s_ashr_i32 s21, s20, 31
	v_sub_u32_e32 v4, v4, v6
	s_lshl_b64 s[20:21], s[20:21], 19
	v_lshlrev_b32_e32 v150, 13, v4
	v_bitop3_b32 v4, v7, v3, 3 bitop3:0x6c
	v_bitop3_b32 v2, v2, v3, 4 bitop3:0x36
	s_add_u32 s20, s34, s20
	v_lshlrev_b32_e32 v5, 12, v5
	v_lshlrev_b32_e32 v4, 3, v4
	v_lshlrev_b32_e32 v2, 3, v2
	s_addc_u32 s21, s35, s21
	v_and_b32_e32 v149, 0xffffc000, v5
	v_lshl_add_u64 v[142:143], s[20:21], 0, v[0:1]
	s_mov_b64 s[60:61], 0
	v_lshlrev_b32_e32 v151, 1, v8
	v_lshlrev_b32_e32 v152, 1, v4
	v_lshlrev_b32_e32 v153, 1, v2
	s_mov_b32 s59, 0
	s_mov_b32 s57, 0
	v_mov_b32_e32 v40, 0
	v_mov_b32_e32 v41, v131
	v_mov_b32_e32 v42, v131
	v_mov_b32_e32 v43, v131
	v_mov_b32_e32 v48, 0
	v_mov_b32_e32 v49, v131
	v_mov_b32_e32 v50, v131
	v_mov_b32_e32 v51, v131
	v_mov_b32_e32 v0, 0
	v_mov_b32_e32 v1, v131
	v_mov_b32_e32 v2, v131
	v_mov_b32_e32 v3, v131
	v_mov_b32_e32 v4, 0
	v_mov_b32_e32 v5, v131
	v_mov_b32_e32 v6, v131
	v_mov_b32_e32 v7, v131
	v_mov_b32_e32 v8, 0
	v_mov_b32_e32 v9, v131
	v_mov_b32_e32 v10, v131
	v_mov_b32_e32 v11, v131
	v_mov_b32_e32 v12, 0
	v_mov_b32_e32 v13, v131
	v_mov_b32_e32 v14, v131
	v_mov_b32_e32 v15, v131
	v_mov_b32_e32 v16, 0
	v_mov_b32_e32 v17, v131
	v_mov_b32_e32 v18, v131
	v_mov_b32_e32 v19, v131
	v_mov_b32_e32 v20, 0
	v_mov_b32_e32 v21, v131
	v_mov_b32_e32 v22, v131
	v_mov_b32_e32 v23, v131
	v_mov_b32_e32 v24, 0
	v_mov_b32_e32 v25, v131
	v_mov_b32_e32 v26, v131
	v_mov_b32_e32 v27, v131
	v_mov_b32_e32 v28, 0
	v_mov_b32_e32 v29, v131
	v_mov_b32_e32 v30, v131
	v_mov_b32_e32 v31, v131
	v_mov_b32_e32 v32, 0
	v_mov_b32_e32 v33, v131
	v_mov_b32_e32 v34, v131
	v_mov_b32_e32 v35, v131
	v_mov_b32_e32 v36, 0
	v_mov_b32_e32 v37, v131
	v_mov_b32_e32 v38, v131
	v_mov_b32_e32 v39, v131
	v_mov_b32_e32 v44, 0
	v_mov_b32_e32 v45, v131
	v_mov_b32_e32 v46, v131
	v_mov_b32_e32 v47, v131
	v_mov_b32_e32 v52, 0
	v_mov_b32_e32 v53, v131
	v_mov_b32_e32 v54, v131
	v_mov_b32_e32 v55, v131
	v_mov_b32_e32 v56, 0
	v_mov_b32_e32 v57, v131
	v_mov_b32_e32 v58, v131
	v_mov_b32_e32 v59, v131
	v_mov_b32_e32 v60, 0
	v_mov_b32_e32 v61, v131
	v_mov_b32_e32 v62, v131
	v_mov_b32_e32 v63, v131
	v_mov_b32_e32 v64, 0
	v_mov_b32_e32 v65, v131
	v_mov_b32_e32 v66, v131
	v_mov_b32_e32 v67, v131
	v_mov_b32_e32 v68, 0
	v_mov_b32_e32 v69, v131
	v_mov_b32_e32 v70, v131
	v_mov_b32_e32 v71, v131
	v_mov_b32_e32 v72, 0
	v_mov_b32_e32 v73, v131
	v_mov_b32_e32 v74, v131
	v_mov_b32_e32 v75, v131
	v_mov_b32_e32 v76, 0
	v_mov_b32_e32 v77, v131
	v_mov_b32_e32 v78, v131
	v_mov_b32_e32 v79, v131
	v_mov_b32_e32 v80, 0
	v_mov_b32_e32 v81, v131
	v_mov_b32_e32 v82, v131
	v_mov_b32_e32 v83, v131
	v_mov_b32_e32 v84, 0
	v_mov_b32_e32 v85, v131
	v_mov_b32_e32 v86, v131
	v_mov_b32_e32 v87, v131
	v_mov_b32_e32 v88, 0
	v_mov_b32_e32 v89, v131
	v_mov_b32_e32 v90, v131
	v_mov_b32_e32 v91, v131
	v_mov_b32_e32 v92, 0
	v_mov_b32_e32 v93, v131
	v_mov_b32_e32 v94, v131
	v_mov_b32_e32 v95, v131
	v_mov_b32_e32 v96, 0
	v_mov_b32_e32 v97, v131
	v_mov_b32_e32 v98, v131
	v_mov_b32_e32 v99, v131
	v_mov_b32_e32 v100, 0
	v_mov_b32_e32 v101, v131
	v_mov_b32_e32 v102, v131
	v_mov_b32_e32 v103, v131
	v_mov_b32_e32 v104, 0
	v_mov_b32_e32 v105, v131
	v_mov_b32_e32 v106, v131
	v_mov_b32_e32 v107, v131
	v_mov_b32_e32 v108, 0
	v_mov_b32_e32 v109, v131
	v_mov_b32_e32 v110, v131
	v_mov_b32_e32 v111, v131
	v_mov_b32_e32 v112, 0
	v_mov_b32_e32 v113, v131
	v_mov_b32_e32 v114, v131
	v_mov_b32_e32 v115, v131
	v_mov_b32_e32 v116, 0
	v_mov_b32_e32 v117, v131
	v_mov_b32_e32 v118, v131
	v_mov_b32_e32 v119, v131
	v_mov_b32_e32 v120, 0
	v_mov_b32_e32 v121, v131
	v_mov_b32_e32 v122, v131
	v_mov_b32_e32 v123, v131
	v_mov_b32_e32 v124, 0
	v_mov_b32_e32 v125, v131
	v_mov_b32_e32 v126, v131
	v_mov_b32_e32 v127, v131
	s_waitcnt vmcnt(0) lgkmcnt(0)
	s_barrier
	v_add3_u32 v180, v149, v151, v152
	v_add3_u32 v223, v150, v151, v152
	v_add3_u32 v222, v149, v151, v153
	v_add3_u32 v224, v150, v151, v153
	v_readfirstlane_b32 s59, v130
	ds_read_b128 v[154:157], v180
	ds_read_b128 v[158:161], v180 offset:2048
	ds_read_b128 v[162:165], v180 offset:4096
	ds_read_b128 v[166:169], v180 offset:6144
	ds_read_b128 v[190:193], v223 offset:32768
	ds_read_b128 v[194:197], v223 offset:34816
	ds_read_b128 v[198:201], v223 offset:36864
	ds_read_b128 v[202:205], v223 offset:38912
	s_mov_b32 s57, 0
	s_mov_b64 s[60:61], s[34:35]
	v_subrev_u32_e32 v178, s34, v142
	v_subrev_u32_e32 v179, s34, v140
	v_xor_b32_e32 v225, 0x10000, v180
	v_xor_b32_e32 v226, 0x10000, v222
	v_xor_b32_e32 v227, 0x10000, v223
	v_xor_b32_e32 v228, 0x10000, v224
	s_add_u32 s59, s59, 0x10000
	s_mov_b32 m0, s59
	s_add_u32 s62, s60, s22
	s_addc_u32 s63, s61, s23
	global_load_lds_dwordx4 v178, s[62:63]
	s_add_u32 m0, s59, 0x2000
	s_add_u32 s62, s60, s36
	s_addc_u32 s63, s61, s37
	global_load_lds_dwordx4 v178, s[62:63]
	s_add_u32 m0, s59, 0x4000
	s_add_u32 s62, s60, s38
	s_addc_u32 s63, s61, s39
	global_load_lds_dwordx4 v178, s[62:63]
	s_add_u32 m0, s59, 0x6000
	s_add_u32 s62, s60, s40
	s_addc_u32 s63, s61, s41
	global_load_lds_dwordx4 v178, s[62:63]
	s_add_u32 m0, s59, 0x8000
	s_add_u32 s62, s60, s42
	s_addc_u32 s63, s61, s43
	global_load_lds_dwordx4 v179, s[62:63]
	s_add_u32 m0, s59, 0xa000
	s_add_u32 s62, s60, s44
	s_addc_u32 s63, s61, s45
	global_load_lds_dwordx4 v179, s[62:63]
	s_add_u32 m0, s59, 0xc000
	s_add_u32 s62, s60, s46
	s_addc_u32 s63, s61, s47
	global_load_lds_dwordx4 v179, s[62:63]
	s_add_u32 m0, s59, 0xe000
	s_add_u32 s62, s60, s48
	s_addc_u32 s63, s61, s49
	global_load_lds_dwordx4 v179, s[62:63]
	s_branch .Lg8_entry

.LBB0_1331:
	s_ashr_i32 s20, s58, 2
	v_mov_b32_e32 v6, v181
	s_and_b32 s4, s58, 7
	s_and_b32 s47, s20, -8
	s_or_b32 s42, s47, s4
	v_lshrrev_b32_e32 v7, 4, v6
	v_lshlrev_b32_e32 v1, 6, v6
	v_xor_b32_e32 v0, v7, v6
	v_and_b32_e32 v8, 0x3c0, v1
	v_lshlrev_b32_e32 v1, 8, v6
	s_ashr_i32 s43, s42, 31
	v_lshlrev_b32_e32 v0, 3, v0
	v_and_b32_e32 v1, 0xfffff800, v1
	s_and_b32 s46, s57, 7
	s_bfe_u32 s4, s58, 0x20003
	s_lshl_b64 s[20:21], s[42:43], 20
	v_and_or_b32 v0, v0, 56, v1
	s_add_u32 s20, s3, s20
	v_ashrrev_i32_e32 v1, 31, v0
	s_addc_u32 s21, s48, s21
	v_lshlrev_b64 v[0:1], 1, v[0:1]
	v_lshl_add_u32 v134, v6, 4, 0
	v_lshl_add_u64 v[2:3], s[20:21], 0, v[0:1]
	v_readfirstlane_b32 s20, v134
	v_add_u32_e32 v9, 0x2000, v134
	s_mov_b32 m0, s20
	v_readfirstlane_b32 s20, v9
	v_add_u32_e32 v9, 0x4000, v134
	s_waitcnt vmcnt(63) expcnt(7) lgkmcnt(15)
	s_barrier
	global_load_lds_dwordx4 v[2:3], off
	v_lshl_add_u64 v[4:5], v[2:3], 0, s[6:7]
	s_mov_b32 m0, s20
	v_readfirstlane_b32 s20, v9
	global_load_lds_dwordx4 v[4:5], off
	v_lshl_add_u64 v[4:5], v[2:3], 0, s[8:9]
	s_mov_b32 m0, s20
	s_lshl_b32 s43, s4, 20
	global_load_lds_dwordx4 v[4:5], off
	v_add_u32_e32 v4, 0x6000, v134
	s_add_u32 s44, s49, s43
	v_readfirstlane_b32 s20, v4
	v_add_u32_e32 v4, 0x8000, v134
	s_addc_u32 s45, s56, 0
	v_lshl_add_u64 v[2:3], v[2:3], 0, s[10:11]
	s_mov_b32 m0, s20
	v_readfirstlane_b32 s20, v4
	v_add_u32_e32 v9, 0xa000, v134
	global_load_lds_dwordx4 v[2:3], off
	v_lshl_add_u64 v[2:3], s[44:45], 0, v[0:1]
	s_mov_b32 m0, s20
	v_readfirstlane_b32 s20, v9
	v_add_u32_e32 v9, 0xc000, v134
	global_load_lds_dwordx4 v[2:3], off
	v_lshl_add_u64 v[4:5], v[2:3], 0, s[6:7]
	s_mov_b32 m0, s20
	v_readfirstlane_b32 s20, v9
	global_load_lds_dwordx4 v[4:5], off
	v_lshl_add_u64 v[4:5], v[2:3], 0, s[8:9]
	s_mov_b32 m0, s20
	v_lshl_add_u64 v[2:3], v[2:3], 0, s[10:11]
	global_load_lds_dwordx4 v[4:5], off
	v_add_u32_e32 v4, 0xe000, v134
	v_mov_b32_e32 v36, 0
	v_readfirstlane_b32 s20, v4
	s_mov_b32 m0, s20
	v_ashrrev_i32_e32 v4, 6, v6
	global_load_lds_dwordx4 v[2:3], off
	s_or_b32 s20, s47, s46
	v_lshrrev_b32_e32 v5, 30, v4
	s_ashr_i32 s21, s20, 31
	v_add_u32_e32 v5, v4, v5
	s_lshl_b64 s[20:21], s[20:21], 20
	v_bfe_u32 v2, v6, 4, 2
	v_bfe_u32 v3, v6, 1, 3
	v_and_b32_e32 v6, 0x7fffc, v5
	s_add_u32 s20, s34, s20
	v_sub_u32_e32 v4, v4, v6
	s_addc_u32 s21, s35, s21
	v_lshlrev_b32_e32 v136, 13, v4
	v_bitop3_b32 v4, v7, v3, 3 bitop3:0x6c
	v_bitop3_b32 v2, v2, v3, 4 bitop3:0x36
	v_lshl_add_u64 v[130:131], s[20:21], 0, v[0:1]
	s_add_u32 s20, s34, s43
	v_lshlrev_b32_e32 v5, 12, v5
	v_lshlrev_b32_e32 v4, 3, v4
	v_lshlrev_b32_e32 v2, 3, v2
	s_addc_u32 s21, s35, 0
	v_and_b32_e32 v135, 0xffffc000, v5
	v_lshl_add_u64 v[132:133], s[20:21], 0, v[0:1]
	s_mov_b64 s[44:45], 0
	v_lshlrev_b32_e32 v137, 1, v8
	v_lshlrev_b32_e32 v138, 1, v4
	v_lshlrev_b32_e32 v139, 1, v2
	s_mov_b32 s59, 0
	s_mov_b32 s43, 0
	v_mov_b32_e32 v37, v36
	v_mov_b32_e32 v38, v36
	v_mov_b32_e32 v39, v36
	v_mov_b32_e32 v40, v36
	v_mov_b32_e32 v41, v36
	v_mov_b32_e32 v42, v36
	v_mov_b32_e32 v43, v36
	v_mov_b32_e32 v0, v36
	v_mov_b32_e32 v1, v36
	v_mov_b32_e32 v2, v36
	v_mov_b32_e32 v3, v36
	v_mov_b32_e32 v4, v36
	v_mov_b32_e32 v5, v36
	v_mov_b32_e32 v6, v36
	v_mov_b32_e32 v7, v36
	v_mov_b32_e32 v8, v36
	v_mov_b32_e32 v9, v36
	v_mov_b32_e32 v10, v36
	v_mov_b32_e32 v11, v36
	v_mov_b32_e32 v12, v36
	v_mov_b32_e32 v13, v36
	v_mov_b32_e32 v14, v36
	v_mov_b32_e32 v15, v36
	v_mov_b32_e32 v16, v36
	v_mov_b32_e32 v17, v36
	v_mov_b32_e32 v18, v36
	v_mov_b32_e32 v19, v36
	v_mov_b32_e32 v20, v36
	v_mov_b32_e32 v21, v36
	v_mov_b32_e32 v22, v36
	v_mov_b32_e32 v23, v36
	v_mov_b32_e32 v24, v36
	v_mov_b32_e32 v25, v36
	v_mov_b32_e32 v26, v36
	v_mov_b32_e32 v27, v36
	v_mov_b32_e32 v28, v36
	v_mov_b32_e32 v29, v36
	v_mov_b32_e32 v30, v36
	v_mov_b32_e32 v31, v36
	v_mov_b32_e32 v32, v36
	v_mov_b32_e32 v33, v36
	v_mov_b32_e32 v34, v36
	v_mov_b32_e32 v35, v36
	v_mov_b32_e32 v44, v36
	v_mov_b32_e32 v45, v36
	v_mov_b32_e32 v46, v36
	v_mov_b32_e32 v47, v36
	v_mov_b32_e32 v48, v36
	v_mov_b32_e32 v49, v36
	v_mov_b32_e32 v50, v36
	v_mov_b32_e32 v51, v36
	v_mov_b32_e32 v52, v36
	v_mov_b32_e32 v53, v36
	v_mov_b32_e32 v54, v36
	v_mov_b32_e32 v55, v36
	v_mov_b32_e32 v56, v36
	v_mov_b32_e32 v57, v36
	v_mov_b32_e32 v58, v36
	v_mov_b32_e32 v59, v36
	v_mov_b32_e32 v60, v36
	v_mov_b32_e32 v61, v36
	v_mov_b32_e32 v62, v36
	v_mov_b32_e32 v63, v36
	v_mov_b32_e32 v64, v36
	v_mov_b32_e32 v65, v36
	v_mov_b32_e32 v66, v36
	v_mov_b32_e32 v67, v36
	v_mov_b32_e32 v68, v36
	v_mov_b32_e32 v69, v36
	v_mov_b32_e32 v70, v36
	v_mov_b32_e32 v71, v36
	v_mov_b32_e32 v72, v36
	v_mov_b32_e32 v73, v36
	v_mov_b32_e32 v74, v36
	v_mov_b32_e32 v75, v36
	v_mov_b32_e32 v76, v36
	v_mov_b32_e32 v77, v36
	v_mov_b32_e32 v78, v36
	v_mov_b32_e32 v79, v36
	v_mov_b32_e32 v80, v36
	v_mov_b32_e32 v81, v36
	v_mov_b32_e32 v82, v36
	v_mov_b32_e32 v83, v36
	v_mov_b32_e32 v84, v36
	v_mov_b32_e32 v85, v36
	v_mov_b32_e32 v86, v36
	v_mov_b32_e32 v87, v36
	v_mov_b32_e32 v88, v36
	v_mov_b32_e32 v89, v36
	v_mov_b32_e32 v90, v36
	v_mov_b32_e32 v91, v36
	v_mov_b32_e32 v92, v36
	v_mov_b32_e32 v93, v36
	v_mov_b32_e32 v94, v36
	v_mov_b32_e32 v95, v36
	v_mov_b32_e32 v96, v36
	v_mov_b32_e32 v97, v36
	v_mov_b32_e32 v98, v36
	v_mov_b32_e32 v99, v36
	v_mov_b32_e32 v100, v36
	v_mov_b32_e32 v101, v36
	v_mov_b32_e32 v102, v36
	v_mov_b32_e32 v103, v36
	v_mov_b32_e32 v104, v36
	v_mov_b32_e32 v105, v36
	v_mov_b32_e32 v106, v36
	v_mov_b32_e32 v107, v36
	v_mov_b32_e32 v108, v36
	v_mov_b32_e32 v109, v36
	v_mov_b32_e32 v110, v36
	v_mov_b32_e32 v111, v36
	v_mov_b32_e32 v112, v36
	v_mov_b32_e32 v113, v36
	v_mov_b32_e32 v114, v36
	v_mov_b32_e32 v115, v36
	v_mov_b32_e32 v116, v36
	v_mov_b32_e32 v117, v36
	v_mov_b32_e32 v118, v36
	v_mov_b32_e32 v119, v36
	v_mov_b32_e32 v120, v36
	v_mov_b32_e32 v121, v36
	v_mov_b32_e32 v122, v36
	v_mov_b32_e32 v123, v36
	v_mov_b32_e32 v124, v36
	v_mov_b32_e32 v125, v36
	v_mov_b32_e32 v126, v36
	v_mov_b32_e32 v127, v36
	s_waitcnt vmcnt(0) lgkmcnt(0)
	s_barrier
	v_add3_u32 v141, v135, v137, v138
	v_add3_u32 v210, v136, v137, v138
	v_add3_u32 v180, v135, v137, v139
	v_add3_u32 v211, v136, v137, v139
	v_readfirstlane_b32 s59, v134
	ds_read_b128 v[142:145], v141
	ds_read_b128 v[146:149], v141 offset:2048
	ds_read_b128 v[150:153], v141 offset:4096
	ds_read_b128 v[154:157], v141 offset:6144
	ds_read_b128 v[174:177], v210 offset:32768
	ds_read_b128 v[182:185], v210 offset:34816
	ds_read_b128 v[186:189], v210 offset:36864
	ds_read_b128 v[190:193], v210 offset:38912
	s_mov_b32 s43, 0
	s_mov_b64 s[44:45], s[34:35]
	v_subrev_u32_e32 v178, s34, v130
	v_subrev_u32_e32 v179, s34, v132
	v_xor_b32_e32 v212, 0x10000, v141
	v_xor_b32_e32 v213, 0x10000, v180
	v_xor_b32_e32 v214, 0x10000, v210
	v_xor_b32_e32 v215, 0x10000, v211
	s_add_u32 s59, s59, 0x10000
	s_mov_b32 m0, s59
	s_add_u32 s46, s44, s12
	s_addc_u32 s47, s45, s13
	global_load_lds_dwordx4 v178, s[46:47]
	s_add_u32 m0, s59, 0x2000
	s_add_u32 s46, s44, s14
	s_addc_u32 s47, s45, s15
	global_load_lds_dwordx4 v178, s[46:47]
	s_add_u32 m0, s59, 0x4000
	s_add_u32 s46, s44, s16
	s_addc_u32 s47, s45, s17
	global_load_lds_dwordx4 v178, s[46:47]
	s_add_u32 m0, s59, 0x6000
	s_add_u32 s46, s44, s18
	s_addc_u32 s47, s45, s19
	global_load_lds_dwordx4 v178, s[46:47]
	s_add_u32 m0, s59, 0x8000
	s_add_u32 s46, s44, s22
	s_addc_u32 s47, s45, s23
	global_load_lds_dwordx4 v179, s[46:47]
	s_add_u32 m0, s59, 0xa000
	s_add_u32 s46, s44, s36
	s_addc_u32 s47, s45, s37
	global_load_lds_dwordx4 v179, s[46:47]
	s_add_u32 m0, s59, 0xc000
	s_add_u32 s46, s44, s38
	s_addc_u32 s47, s45, s39
	global_load_lds_dwordx4 v179, s[46:47]
	s_add_u32 m0, s59, 0xe000
	s_add_u32 s46, s44, s40
	s_addc_u32 s47, s45, s41
	global_load_lds_dwordx4 v179, s[46:47]
	s_branch .Lg9_entry

.LBB0_1488:
	v_mov_b32_e32 v6, v181
	s_ashr_i32 s51, s50, 6
	v_lshrrev_b32_e32 v7, 4, v6
	v_lshlrev_b32_e32 v1, 6, v6
	v_xor_b32_e32 v0, v7, v6
	v_and_b32_e32 v8, 0x3c0, v1
	v_lshlrev_b32_e32 v1, 7, v6
	s_bfe_u32 s52, s50, 0x20006
	s_and_b32 s56, s49, 63
	s_and_b32 s53, s50, 63
	s_and_b32 s20, s51, -4
	v_lshlrev_b32_e32 v0, 3, v0
	v_and_b32_e32 v1, 0xfffffc00, v1
	s_lshl_b32 s46, s56, 19
	s_or_b32 s42, s20, s52
	s_lshl_b32 s20, s53, 19
	v_and_or_b32 v0, v0, 56, v1
	s_add_u32 s20, s3, s20
	v_ashrrev_i32_e32 v1, 31, v0
	s_addc_u32 s21, s48, 0
	v_lshlrev_b64 v[0:1], 1, v[0:1]
	v_lshl_add_u32 v129, v6, 4, 0
	v_lshl_add_u64 v[2:3], s[20:21], 0, v[0:1]
	v_readfirstlane_b32 s20, v129
	v_add_u32_e32 v9, 0x2000, v129
	s_mov_b32 m0, s20
	v_readfirstlane_b32 s20, v9
	v_add_u32_e32 v9, 0x4000, v129
	s_waitcnt vmcnt(63) expcnt(7) lgkmcnt(15)
	s_barrier
	global_load_lds_dwordx4 v[2:3], off
	v_lshl_add_u64 v[4:5], v[2:3], 0, s[8:9]
	s_mov_b32 m0, s20
	v_readfirstlane_b32 s20, v9
	global_load_lds_dwordx4 v[4:5], off
	v_lshl_add_u64 v[4:5], v[2:3], 0, s[10:11]
	s_mov_b32 m0, s20
	s_ashr_i32 s43, s42, 31
	global_load_lds_dwordx4 v[4:5], off
	v_add_u32_e32 v4, 0x6000, v129
	s_lshl_b64 s[44:45], s[42:43], 19
	v_readfirstlane_b32 s20, v4
	v_lshl_add_u64 v[2:3], v[2:3], 0, s[12:13]
	s_mov_b32 m0, s20
	s_add_u32 s44, s34, s44
	global_load_lds_dwordx4 v[2:3], off
	v_add_u32_e32 v2, 0x8000, v129
	s_addc_u32 s45, s35, s45
	v_readfirstlane_b32 s20, v2
	v_add_u32_e32 v4, 0xa000, v129
	v_lshl_add_u64 v[134:135], s[44:45], 0, v[0:1]
	s_mov_b32 m0, s20
	v_readfirstlane_b32 s20, v4
	v_add_u32_e32 v4, 0xc000, v129
	global_load_lds_dwordx4 v[134:135], off
	v_lshl_add_u64 v[2:3], v[134:135], 0, s[8:9]
	s_mov_b32 m0, s20
	v_readfirstlane_b32 s20, v4
	v_add_u32_e32 v4, 0xe000, v129
	global_load_lds_dwordx4 v[2:3], off
	v_lshl_add_u64 v[2:3], v[134:135], 0, s[10:11]
	s_mov_b32 m0, s20
	v_readfirstlane_b32 s20, v4
	global_load_lds_dwordx4 v[2:3], off
	v_lshl_add_u64 v[2:3], v[134:135], 0, s[12:13]
	s_mov_b32 m0, s20
	v_ashrrev_i32_e32 v4, 6, v6
	global_load_lds_dwordx4 v[2:3], off
	v_lshrrev_b32_e32 v5, 30, v4
	v_add_u32_e32 v5, v4, v5
	v_bfe_u32 v2, v6, 4, 2
	v_bfe_u32 v3, v6, 1, 3
	v_and_b32_e32 v6, 0x7fffc, v5
	v_sub_u32_e32 v4, v4, v6
	v_lshlrev_b32_e32 v139, 13, v4
	v_bitop3_b32 v4, v7, v3, 3 bitop3:0x6c
	v_bitop3_b32 v2, v2, v3, 4 bitop3:0x36
	s_add_u32 s20, s34, s46
	v_lshlrev_b32_e32 v5, 12, v5
	v_lshlrev_b32_e32 v4, 3, v4
	v_lshlrev_b32_e32 v2, 3, v2
	s_addc_u32 s21, s35, 0
	v_and_b32_e32 v138, 0xffffc000, v5
	v_lshl_add_u64 v[136:137], s[20:21], 0, v[0:1]
	s_mov_b64 s[44:45], 0
	s_waitcnt lgkmcnt(0)
	v_lshlrev_b32_e32 v140, 1, v8
	v_lshlrev_b32_e32 v141, 1, v4
	v_lshlrev_b32_e32 v142, 1, v2
	s_mov_b32 s57, 0
	s_mov_b32 s43, 0
	v_mov_b32_e32 v8, v128
	v_mov_b32_e32 v9, v128
	v_mov_b32_e32 v10, v128
	v_mov_b32_e32 v11, v128
	v_mov_b32_e32 v20, v128
	v_mov_b32_e32 v21, v128
	v_mov_b32_e32 v22, v128
	v_mov_b32_e32 v23, v128
	v_mov_b32_e32 v0, v128
	v_mov_b32_e32 v1, v128
	v_mov_b32_e32 v2, v128
	v_mov_b32_e32 v3, v128
	v_mov_b32_e32 v4, v128
	v_mov_b32_e32 v5, v128
	v_mov_b32_e32 v6, v128
	v_mov_b32_e32 v7, v128
	v_mov_b32_e32 v12, v128
	v_mov_b32_e32 v13, v128
	v_mov_b32_e32 v14, v128
	v_mov_b32_e32 v15, v128
	v_mov_b32_e32 v24, v128
	v_mov_b32_e32 v25, v128
	v_mov_b32_e32 v26, v128
	v_mov_b32_e32 v27, v128
	v_mov_b32_e32 v16, v128
	v_mov_b32_e32 v17, v128
	v_mov_b32_e32 v18, v128
	v_mov_b32_e32 v19, v128
	v_mov_b32_e32 v28, v128
	v_mov_b32_e32 v29, v128
	v_mov_b32_e32 v30, v128
	v_mov_b32_e32 v31, v128
	v_mov_b32_e32 v32, v128
	v_mov_b32_e32 v33, v128
	v_mov_b32_e32 v34, v128
	v_mov_b32_e32 v35, v128
	v_mov_b32_e32 v40, v128
	v_mov_b32_e32 v41, v128
	v_mov_b32_e32 v42, v128
	v_mov_b32_e32 v43, v128
	v_mov_b32_e32 v36, v128
	v_mov_b32_e32 v37, v128
	v_mov_b32_e32 v38, v128
	v_mov_b32_e32 v39, v128
	v_mov_b32_e32 v44, v128
	v_mov_b32_e32 v45, v128
	v_mov_b32_e32 v46, v128
	v_mov_b32_e32 v47, v128
	v_mov_b32_e32 v48, v128
	v_mov_b32_e32 v49, v128
	v_mov_b32_e32 v50, v128
	v_mov_b32_e32 v51, v128
	v_mov_b32_e32 v56, v128
	v_mov_b32_e32 v57, v128
	v_mov_b32_e32 v58, v128
	v_mov_b32_e32 v59, v128
	v_mov_b32_e32 v52, v128
	v_mov_b32_e32 v53, v128
	v_mov_b32_e32 v54, v128
	v_mov_b32_e32 v55, v128
	v_mov_b32_e32 v60, v128
	v_mov_b32_e32 v61, v128
	v_mov_b32_e32 v62, v128
	v_mov_b32_e32 v63, v128
	v_mov_b32_e32 v64, v128
	v_mov_b32_e32 v65, v128
	v_mov_b32_e32 v66, v128
	v_mov_b32_e32 v67, v128
	v_mov_b32_e32 v72, v128
	v_mov_b32_e32 v73, v128
	v_mov_b32_e32 v74, v128
	v_mov_b32_e32 v75, v128
	v_mov_b32_e32 v68, v128
	v_mov_b32_e32 v69, v128
	v_mov_b32_e32 v70, v128
	v_mov_b32_e32 v71, v128
	v_mov_b32_e32 v76, v128
	v_mov_b32_e32 v77, v128
	v_mov_b32_e32 v78, v128
	v_mov_b32_e32 v79, v128
	v_mov_b32_e32 v80, v128
	v_mov_b32_e32 v81, v128
	v_mov_b32_e32 v82, v128
	v_mov_b32_e32 v83, v128
	v_mov_b32_e32 v88, v128
	v_mov_b32_e32 v89, v128
	v_mov_b32_e32 v90, v128
	v_mov_b32_e32 v91, v128
	v_mov_b32_e32 v84, v128
	v_mov_b32_e32 v85, v128
	v_mov_b32_e32 v86, v128
	v_mov_b32_e32 v87, v128
	v_mov_b32_e32 v92, v128
	v_mov_b32_e32 v93, v128
	v_mov_b32_e32 v94, v128
	v_mov_b32_e32 v95, v128
	v_mov_b32_e32 v96, v128
	v_mov_b32_e32 v97, v128
	v_mov_b32_e32 v98, v128
	v_mov_b32_e32 v99, v128
	v_mov_b32_e32 v104, v128
	v_mov_b32_e32 v105, v128
	v_mov_b32_e32 v106, v128
	v_mov_b32_e32 v107, v128
	v_mov_b32_e32 v100, v128
	v_mov_b32_e32 v101, v128
	v_mov_b32_e32 v102, v128
	v_mov_b32_e32 v103, v128
	v_mov_b32_e32 v108, v128
	v_mov_b32_e32 v109, v128
	v_mov_b32_e32 v110, v128
	v_mov_b32_e32 v111, v128
	v_mov_b32_e32 v112, v128
	v_mov_b32_e32 v113, v128
	v_mov_b32_e32 v114, v128
	v_mov_b32_e32 v115, v128
	v_mov_b32_e32 v120, v128
	v_mov_b32_e32 v121, v128
	v_mov_b32_e32 v122, v128
	v_mov_b32_e32 v123, v128
	v_mov_b32_e32 v116, v128
	v_mov_b32_e32 v117, v128
	v_mov_b32_e32 v118, v128
	v_mov_b32_e32 v119, v128
	v_mov_b32_e32 v124, v128
	v_mov_b32_e32 v125, v128
	v_mov_b32_e32 v126, v128
	v_mov_b32_e32 v127, v128
	s_waitcnt vmcnt(0) lgkmcnt(0)
	s_barrier
	v_add3_u32 v143, v138, v140, v141
	v_add3_u32 v180, v139, v140, v141
	v_add3_u32 v155, v138, v140, v142
	v_add3_u32 v222, v139, v140, v142
	v_readfirstlane_b32 s57, v129
	ds_read_b128 v[156:159], v143
	ds_read_b128 v[160:163], v143 offset:2048
	ds_read_b128 v[164:167], v143 offset:4096
	ds_read_b128 v[168:171], v143 offset:6144
	ds_read_b128 v[190:193], v180 offset:32768
	ds_read_b128 v[194:197], v180 offset:34816
	ds_read_b128 v[198:201], v180 offset:36864
	ds_read_b128 v[202:205], v180 offset:38912
	s_mov_b32 s43, 0
	s_mov_b64 s[44:45], s[34:35]
	v_subrev_u32_e32 v144, s34, v136
	v_subrev_u32_e32 v145, s34, v134
	v_xor_b32_e32 v223, 0x10000, v143
	v_xor_b32_e32 v224, 0x10000, v155
	v_xor_b32_e32 v225, 0x10000, v180
	v_xor_b32_e32 v226, 0x10000, v222
	s_add_u32 s57, s57, 0x10000
	s_mov_b32 m0, s57
	s_add_u32 s46, s44, s14
	s_addc_u32 s47, s45, s15
	global_load_lds_dwordx4 v144, s[46:47]
	s_add_u32 m0, s57, 0x2000
	s_add_u32 s46, s44, s16
	s_addc_u32 s47, s45, s17
	global_load_lds_dwordx4 v144, s[46:47]
	s_add_u32 m0, s57, 0x4000
	s_add_u32 s46, s44, s18
	s_addc_u32 s47, s45, s19
	global_load_lds_dwordx4 v144, s[46:47]
	s_add_u32 m0, s57, 0x6000
	s_add_u32 s46, s44, s22
	s_addc_u32 s47, s45, s23
	global_load_lds_dwordx4 v144, s[46:47]
	s_add_u32 m0, s57, 0x8000
	s_add_u32 s46, s44, s30
	s_addc_u32 s47, s45, s31
	global_load_lds_dwordx4 v145, s[46:47]
	s_add_u32 m0, s57, 0xa000
	s_add_u32 s46, s44, s36
	s_addc_u32 s47, s45, s37
	global_load_lds_dwordx4 v145, s[46:47]
	s_add_u32 m0, s57, 0xc000
	s_add_u32 s46, s44, s38
	s_addc_u32 s47, s45, s39
	global_load_lds_dwordx4 v145, s[46:47]
	s_add_u32 m0, s57, 0xe000
	s_add_u32 s46, s44, s40
	s_addc_u32 s47, s45, s41
	global_load_lds_dwordx4 v145, s[46:47]
	s_branch .Lg10_entry

.LBB0_1636:
	s_ashr_i32 s20, s44, 2
	v_mov_b32_e32 v6, v181
	s_and_b32 s4, s44, 7
	s_and_b32 s39, s20, -8
	s_or_b32 s30, s39, s4
	v_lshrrev_b32_e32 v7, 4, v6
	v_lshlrev_b32_e32 v1, 6, v6
	v_xor_b32_e32 v0, v7, v6
	v_and_b32_e32 v8, 0x3c0, v1
	v_lshlrev_b32_e32 v1, 8, v6
	s_ashr_i32 s31, s30, 31
	v_lshlrev_b32_e32 v0, 3, v0
	v_and_b32_e32 v1, 0xfffff800, v1
	s_and_b32 s38, s43, 7
	s_bfe_u32 s4, s44, 0x20003
	s_lshl_b64 s[20:21], s[30:31], 20
	v_and_or_b32 v0, v0, 56, v1
	s_add_u32 s20, s3, s20
	v_ashrrev_i32_e32 v1, 31, v0
	s_addc_u32 s21, s40, s21
	v_lshlrev_b64 v[0:1], 1, v[0:1]
	v_lshl_add_u32 v134, v6, 4, 0
	v_lshl_add_u64 v[2:3], s[20:21], 0, v[0:1]
	v_readfirstlane_b32 s20, v134
	v_add_u32_e32 v9, 0x2000, v134
	s_mov_b32 m0, s20
	v_readfirstlane_b32 s20, v9
	v_add_u32_e32 v9, 0x4000, v134
	s_waitcnt vmcnt(63) expcnt(7) lgkmcnt(15)
	s_barrier
	global_load_lds_dwordx4 v[2:3], off
	v_lshl_add_u64 v[4:5], v[2:3], 0, s[6:7]
	s_mov_b32 m0, s20
	v_readfirstlane_b32 s20, v9
	global_load_lds_dwordx4 v[4:5], off
	v_lshl_add_u64 v[4:5], v[2:3], 0, s[8:9]
	s_mov_b32 m0, s20
	s_lshl_b32 s31, s4, 20
	global_load_lds_dwordx4 v[4:5], off
	v_add_u32_e32 v4, 0x6000, v134
	s_add_u32 s36, s41, s31
	v_readfirstlane_b32 s20, v4
	v_add_u32_e32 v4, 0x8000, v134
	s_addc_u32 s37, s42, 0
	v_lshl_add_u64 v[2:3], v[2:3], 0, s[10:11]
	s_mov_b32 m0, s20
	v_readfirstlane_b32 s20, v4
	v_add_u32_e32 v9, 0xa000, v134
	global_load_lds_dwordx4 v[2:3], off
	v_lshl_add_u64 v[2:3], s[36:37], 0, v[0:1]
	s_mov_b32 m0, s20
	v_readfirstlane_b32 s20, v9
	v_add_u32_e32 v9, 0xc000, v134
	global_load_lds_dwordx4 v[2:3], off
	v_lshl_add_u64 v[4:5], v[2:3], 0, s[6:7]
	s_mov_b32 m0, s20
	v_readfirstlane_b32 s20, v9
	global_load_lds_dwordx4 v[4:5], off
	v_lshl_add_u64 v[4:5], v[2:3], 0, s[8:9]
	s_mov_b32 m0, s20
	v_lshl_add_u64 v[2:3], v[2:3], 0, s[10:11]
	global_load_lds_dwordx4 v[4:5], off
	v_add_u32_e32 v4, 0xe000, v134
	v_mov_b32_e32 v36, 0
	v_readfirstlane_b32 s20, v4
	s_mov_b32 m0, s20
	v_ashrrev_i32_e32 v4, 6, v6
	global_load_lds_dwordx4 v[2:3], off
	s_or_b32 s20, s39, s38
	v_lshrrev_b32_e32 v5, 30, v4
	s_ashr_i32 s21, s20, 31
	v_add_u32_e32 v5, v4, v5
	s_lshl_b64 s[20:21], s[20:21], 20
	v_bfe_u32 v2, v6, 4, 2
	v_bfe_u32 v3, v6, 1, 3
	v_and_b32_e32 v6, 0x7fffc, v5
	s_add_u32 s20, s34, s20
	v_sub_u32_e32 v4, v4, v6
	s_addc_u32 s21, s35, s21
	v_lshlrev_b32_e32 v136, 13, v4
	v_bitop3_b32 v4, v7, v3, 3 bitop3:0x6c
	v_bitop3_b32 v2, v2, v3, 4 bitop3:0x36
	v_lshl_add_u64 v[130:131], s[20:21], 0, v[0:1]
	s_add_u32 s20, s34, s31
	v_lshlrev_b32_e32 v5, 12, v5
	v_lshlrev_b32_e32 v4, 3, v4
	v_lshlrev_b32_e32 v2, 3, v2
	s_addc_u32 s21, s35, 0
	v_and_b32_e32 v135, 0xffffc000, v5
	v_lshl_add_u64 v[132:133], s[20:21], 0, v[0:1]
	s_mov_b64 s[36:37], 0
	v_lshlrev_b32_e32 v137, 1, v8
	v_lshlrev_b32_e32 v138, 1, v4
	v_lshlrev_b32_e32 v139, 1, v2
	s_mov_b32 s45, 0
	s_mov_b32 s31, 0
	v_mov_b32_e32 v37, v36
	v_mov_b32_e32 v38, v36
	v_mov_b32_e32 v39, v36
	v_mov_b32_e32 v40, v36
	v_mov_b32_e32 v41, v36
	v_mov_b32_e32 v42, v36
	v_mov_b32_e32 v43, v36
	v_mov_b32_e32 v0, v36
	v_mov_b32_e32 v1, v36
	v_mov_b32_e32 v2, v36
	v_mov_b32_e32 v3, v36
	v_mov_b32_e32 v4, v36
	v_mov_b32_e32 v5, v36
	v_mov_b32_e32 v6, v36
	v_mov_b32_e32 v7, v36
	v_mov_b32_e32 v8, v36
	v_mov_b32_e32 v9, v36
	v_mov_b32_e32 v10, v36
	v_mov_b32_e32 v11, v36
	v_mov_b32_e32 v12, v36
	v_mov_b32_e32 v13, v36
	v_mov_b32_e32 v14, v36
	v_mov_b32_e32 v15, v36
	v_mov_b32_e32 v16, v36
	v_mov_b32_e32 v17, v36
	v_mov_b32_e32 v18, v36
	v_mov_b32_e32 v19, v36
	v_mov_b32_e32 v20, v36
	v_mov_b32_e32 v21, v36
	v_mov_b32_e32 v22, v36
	v_mov_b32_e32 v23, v36
	v_mov_b32_e32 v24, v36
	v_mov_b32_e32 v25, v36
	v_mov_b32_e32 v26, v36
	v_mov_b32_e32 v27, v36
	v_mov_b32_e32 v28, v36
	v_mov_b32_e32 v29, v36
	v_mov_b32_e32 v30, v36
	v_mov_b32_e32 v31, v36
	v_mov_b32_e32 v32, v36
	v_mov_b32_e32 v33, v36
	v_mov_b32_e32 v34, v36
	v_mov_b32_e32 v35, v36
	v_mov_b32_e32 v44, v36
	v_mov_b32_e32 v45, v36
	v_mov_b32_e32 v46, v36
	v_mov_b32_e32 v47, v36
	v_mov_b32_e32 v48, v36
	v_mov_b32_e32 v49, v36
	v_mov_b32_e32 v50, v36
	v_mov_b32_e32 v51, v36
	v_mov_b32_e32 v52, v36
	v_mov_b32_e32 v53, v36
	v_mov_b32_e32 v54, v36
	v_mov_b32_e32 v55, v36
	v_mov_b32_e32 v56, v36
	v_mov_b32_e32 v57, v36
	v_mov_b32_e32 v58, v36
	v_mov_b32_e32 v59, v36
	v_mov_b32_e32 v60, v36
	v_mov_b32_e32 v61, v36
	v_mov_b32_e32 v62, v36
	v_mov_b32_e32 v63, v36
	v_mov_b32_e32 v64, v36
	v_mov_b32_e32 v65, v36
	v_mov_b32_e32 v66, v36
	v_mov_b32_e32 v67, v36
	v_mov_b32_e32 v68, v36
	v_mov_b32_e32 v69, v36
	v_mov_b32_e32 v70, v36
	v_mov_b32_e32 v71, v36
	v_mov_b32_e32 v72, v36
	v_mov_b32_e32 v73, v36
	v_mov_b32_e32 v74, v36
	v_mov_b32_e32 v75, v36
	v_mov_b32_e32 v76, v36
	v_mov_b32_e32 v77, v36
	v_mov_b32_e32 v78, v36
	v_mov_b32_e32 v79, v36
	v_mov_b32_e32 v80, v36
	v_mov_b32_e32 v81, v36
	v_mov_b32_e32 v82, v36
	v_mov_b32_e32 v83, v36
	v_mov_b32_e32 v84, v36
	v_mov_b32_e32 v85, v36
	v_mov_b32_e32 v86, v36
	v_mov_b32_e32 v87, v36
	v_mov_b32_e32 v88, v36
	v_mov_b32_e32 v89, v36
	v_mov_b32_e32 v90, v36
	v_mov_b32_e32 v91, v36
	v_mov_b32_e32 v92, v36
	v_mov_b32_e32 v93, v36
	v_mov_b32_e32 v94, v36
	v_mov_b32_e32 v95, v36
	v_mov_b32_e32 v96, v36
	v_mov_b32_e32 v97, v36
	v_mov_b32_e32 v98, v36
	v_mov_b32_e32 v99, v36
	v_mov_b32_e32 v100, v36
	v_mov_b32_e32 v101, v36
	v_mov_b32_e32 v102, v36
	v_mov_b32_e32 v103, v36
	v_mov_b32_e32 v104, v36
	v_mov_b32_e32 v105, v36
	v_mov_b32_e32 v106, v36
	v_mov_b32_e32 v107, v36
	v_mov_b32_e32 v108, v36
	v_mov_b32_e32 v109, v36
	v_mov_b32_e32 v110, v36
	v_mov_b32_e32 v111, v36
	v_mov_b32_e32 v112, v36
	v_mov_b32_e32 v113, v36
	v_mov_b32_e32 v114, v36
	v_mov_b32_e32 v115, v36
	v_mov_b32_e32 v116, v36
	v_mov_b32_e32 v117, v36
	v_mov_b32_e32 v118, v36
	v_mov_b32_e32 v119, v36
	v_mov_b32_e32 v120, v36
	v_mov_b32_e32 v121, v36
	v_mov_b32_e32 v122, v36
	v_mov_b32_e32 v123, v36
	v_mov_b32_e32 v124, v36
	v_mov_b32_e32 v125, v36
	v_mov_b32_e32 v126, v36
	v_mov_b32_e32 v127, v36
	s_waitcnt vmcnt(0) lgkmcnt(0)
	s_barrier
	v_add3_u32 v141, v135, v137, v138
	v_add3_u32 v210, v136, v137, v138
	v_add3_u32 v180, v135, v137, v139
	v_add3_u32 v211, v136, v137, v139
	v_readfirstlane_b32 s45, v134
	ds_read_b128 v[142:145], v141
	ds_read_b128 v[146:149], v141 offset:2048
	ds_read_b128 v[150:153], v141 offset:4096
	ds_read_b128 v[154:157], v141 offset:6144
	ds_read_b128 v[174:177], v210 offset:32768
	ds_read_b128 v[182:185], v210 offset:34816
	ds_read_b128 v[186:189], v210 offset:36864
	ds_read_b128 v[190:193], v210 offset:38912
	s_mov_b32 s31, 0
	s_mov_b64 s[36:37], s[34:35]
	v_subrev_u32_e32 v178, s34, v130
	v_subrev_u32_e32 v179, s34, v132
	v_xor_b32_e32 v212, 0x10000, v141
	v_xor_b32_e32 v213, 0x10000, v180
	v_xor_b32_e32 v214, 0x10000, v210
	v_xor_b32_e32 v215, 0x10000, v211
	s_add_u32 s45, s45, 0x10000
	s_mov_b32 m0, s45
	s_add_u32 s38, s36, s12
	s_addc_u32 s39, s37, s13
	global_load_lds_dwordx4 v178, s[38:39]
	s_add_u32 m0, s45, 0x2000
	s_add_u32 s38, s36, s14
	s_addc_u32 s39, s37, s15
	global_load_lds_dwordx4 v178, s[38:39]
	s_add_u32 m0, s45, 0x4000
	s_add_u32 s38, s36, s16
	s_addc_u32 s39, s37, s17
	global_load_lds_dwordx4 v178, s[38:39]
	s_add_u32 m0, s45, 0x6000
	s_add_u32 s38, s36, s18
	s_addc_u32 s39, s37, s19
	global_load_lds_dwordx4 v178, s[38:39]
	s_add_u32 m0, s45, 0x8000
	s_add_u32 s38, s36, s22
	s_addc_u32 s39, s37, s23
	global_load_lds_dwordx4 v179, s[38:39]
	s_add_u32 m0, s45, 0xa000
	s_add_u32 s38, s36, s24
	s_addc_u32 s39, s37, s25
	global_load_lds_dwordx4 v179, s[38:39]
	s_add_u32 m0, s45, 0xc000
	s_add_u32 s38, s36, s26
	s_addc_u32 s39, s37, s27
	global_load_lds_dwordx4 v179, s[38:39]
	s_add_u32 m0, s45, 0xe000
	s_add_u32 s38, s36, s28
	s_addc_u32 s39, s37, s29
	global_load_lds_dwordx4 v179, s[38:39]
	s_branch .Lg11_entry
